# GEMM K-loops: removed only the repeated lgkmcnt(0) after each barrier
# baseline (speedup 1.0000x reference)
.LBB0_196:
	s_add_u32 s12, s40, 0xfff00080
	s_addc_u32 s13, s41, -1
	s_add_i32 s76, 0, 0x10000
	s_cmp_eq_u32 s75, 60
	s_cselect_b32 s43, s10, s13
	s_cselect_b32 s42, s11, s12
	s_cselect_b32 s25, s63, s74
	s_cselect_b32 s24, s72, s73
	s_add_i32 s12, 0, 0x14000
	v_add_u32_e32 v140, s76, v223
	v_add_u32_e32 v156, s12, v223
	ds_read_b128 v[128:131], v140
	ds_read_b128 v[132:135], v140 offset:1024
	ds_read_b128 v[136:139], v140 offset:2048
	ds_read_b128 v[140:143], v140 offset:3072
	ds_read_b128 v[144:147], v156
	ds_read_b128 v[148:151], v156 offset:1024
	ds_read_b128 v[152:155], v156 offset:2048
	ds_read_b128 v[156:159], v156 offset:3072
	v_lshl_add_u64 v[194:195], s[40:41], 0, v[206:207]
	s_add_i32 m0, s4, 0xc000
	ds_read_b128 v[160:163], v224
	ds_read_b128 v[164:167], v224 offset:1024
	ds_read_b128 v[168:171], v224 offset:2048
	ds_read_b128 v[172:175], v224 offset:3072
	ds_read_b128 v[176:179], v224 offset:4096
	ds_read_b128 v[180:183], v224 offset:5120
	ds_read_b128 v[184:187], v224 offset:6144
	ds_read_b128 v[188:191], v224 offset:7168
	global_load_lds_dwordx4 v[194:195], off
	v_lshl_add_u64 v[194:195], s[40:41], 0, v[208:209]
	s_add_i32 m0, s4, 0xe000
	s_nop 0
	global_load_lds_dwordx4 v[194:195], off
	s_waitcnt vmcnt(8)
	s_waitcnt lgkmcnt(0)
	s_barrier
	s_setprio 1
	v_mfma_f32_16x16x32_bf16 v[124:127], v[128:131], v[160:163], v[124:127]
	v_mfma_f32_16x16x32_bf16 v[120:123], v[136:139], v[160:163], v[120:123]
	v_mfma_f32_16x16x32_bf16 v[108:111], v[128:131], v[168:171], v[108:111]
	v_mfma_f32_16x16x32_bf16 v[104:107], v[136:139], v[168:171], v[104:107]
	v_mfma_f32_16x16x32_bf16 v[92:95], v[128:131], v[176:179], v[92:95]
	v_mfma_f32_16x16x32_bf16 v[88:91], v[136:139], v[176:179], v[88:91]
	v_mfma_f32_16x16x32_bf16 v[76:79], v[128:131], v[184:187], v[76:79]
	v_mfma_f32_16x16x32_bf16 v[72:75], v[136:139], v[184:187], v[72:75]
	v_mfma_f32_16x16x32_bf16 v[124:127], v[132:135], v[164:167], v[124:127]
	v_mfma_f32_16x16x32_bf16 v[120:123], v[140:143], v[164:167], v[120:123]
	v_mfma_f32_16x16x32_bf16 v[108:111], v[132:135], v[172:175], v[108:111]
	v_mfma_f32_16x16x32_bf16 v[104:107], v[140:143], v[172:175], v[104:107]
	v_mfma_f32_16x16x32_bf16 v[92:95], v[132:135], v[180:183], v[92:95]
	v_mfma_f32_16x16x32_bf16 v[88:91], v[140:143], v[180:183], v[88:91]
	v_mfma_f32_16x16x32_bf16 v[76:79], v[132:135], v[188:191], v[76:79]
	v_mfma_f32_16x16x32_bf16 v[72:75], v[140:143], v[188:191], v[72:75]
	s_setprio 0
	s_setprio 1
	v_mfma_f32_16x16x32_bf16 v[116:119], v[144:147], v[160:163], v[116:119]
	v_mfma_f32_16x16x32_bf16 v[112:115], v[152:155], v[160:163], v[112:115]
	v_mfma_f32_16x16x32_bf16 v[100:103], v[144:147], v[168:171], v[100:103]
	v_mfma_f32_16x16x32_bf16 v[96:99], v[152:155], v[168:171], v[96:99]
	v_mfma_f32_16x16x32_bf16 v[84:87], v[144:147], v[176:179], v[84:87]
	v_mfma_f32_16x16x32_bf16 v[80:83], v[152:155], v[176:179], v[80:83]
	v_mfma_f32_16x16x32_bf16 v[68:71], v[144:147], v[184:187], v[68:71]
	v_mfma_f32_16x16x32_bf16 v[64:67], v[152:155], v[184:187], v[64:67]
	v_mfma_f32_16x16x32_bf16 v[116:119], v[148:151], v[164:167], v[116:119]
	v_mfma_f32_16x16x32_bf16 v[112:115], v[156:159], v[164:167], v[112:115]
	v_mfma_f32_16x16x32_bf16 v[100:103], v[148:151], v[172:175], v[100:103]
	v_mfma_f32_16x16x32_bf16 v[96:99], v[156:159], v[172:175], v[96:99]
	v_mfma_f32_16x16x32_bf16 v[84:87], v[148:151], v[180:183], v[84:87]
	v_mfma_f32_16x16x32_bf16 v[80:83], v[156:159], v[180:183], v[80:83]
	v_mfma_f32_16x16x32_bf16 v[68:71], v[148:151], v[188:191], v[68:71]
	v_mfma_f32_16x16x32_bf16 v[64:67], v[156:159], v[188:191], v[64:67]
	s_setprio 0
	s_barrier
	s_add_i32 s13, s76, s0
	v_lshl_add_u64 v[194:195], s[24:25], 0, v[202:203]
	s_mov_b32 m0, s13
	ds_read_b128 v[160:163], v224 offset:16384
	ds_read_b128 v[164:167], v224 offset:17408
	ds_read_b128 v[168:171], v224 offset:18432
	ds_read_b128 v[172:175], v224 offset:19456
	ds_read_b128 v[176:179], v224 offset:20480
	ds_read_b128 v[180:183], v224 offset:21504
	ds_read_b128 v[184:187], v224 offset:22528
	ds_read_b128 v[188:191], v224 offset:23552
	global_load_lds_dwordx4 v[194:195], off
	s_add_i32 m0, s13, 0x2000
	s_add_u32 s76, s24, 0x100000
	v_lshl_add_u64 v[196:197], s[24:25], 0, v[198:199]
	s_addc_u32 s77, s25, 0
	s_add_i32 s12, s12, s0
	global_load_lds_dwordx4 v[196:197], off
	v_lshl_add_u64 v[210:211], s[76:77], 0, v[202:203]
	s_mov_b32 m0, s12
	v_lshl_add_u64 v[212:213], s[42:43], 0, v[200:201]
	global_load_lds_dwordx4 v[210:211], off
	v_lshl_add_u64 v[210:211], s[76:77], 0, v[198:199]
	s_add_i32 m0, s12, 0x2000
	s_nop 0
	global_load_lds_dwordx4 v[210:211], off
	v_lshl_add_u64 v[210:211], s[42:43], 0, v[204:205]
	s_mov_b32 m0, s4
	s_nop 0
	global_load_lds_dwordx4 v[210:211], off
	s_mov_b32 m0, s5
	s_nop 0
	global_load_lds_dwordx4 v[212:213], off
	s_waitcnt vmcnt(8)
	s_waitcnt lgkmcnt(0)
	s_barrier
	s_setprio 1
	v_mfma_f32_16x16x32_bf16 v[60:63], v[128:131], v[160:163], v[60:63]
	v_mfma_f32_16x16x32_bf16 v[56:59], v[136:139], v[160:163], v[56:59]
	v_mfma_f32_16x16x32_bf16 v[44:47], v[128:131], v[168:171], v[44:47]
	v_mfma_f32_16x16x32_bf16 v[40:43], v[136:139], v[168:171], v[40:43]
	v_mfma_f32_16x16x32_bf16 v[28:31], v[128:131], v[176:179], v[28:31]
	v_mfma_f32_16x16x32_bf16 v[24:27], v[136:139], v[176:179], v[24:27]
	v_mfma_f32_16x16x32_bf16 v[12:15], v[128:131], v[184:187], v[12:15]
	v_mfma_f32_16x16x32_bf16 v[8:11], v[136:139], v[184:187], v[8:11]
	v_mfma_f32_16x16x32_bf16 v[60:63], v[132:135], v[164:167], v[60:63]
	v_mfma_f32_16x16x32_bf16 v[56:59], v[140:143], v[164:167], v[56:59]
	v_mfma_f32_16x16x32_bf16 v[44:47], v[132:135], v[172:175], v[44:47]
	v_mfma_f32_16x16x32_bf16 v[40:43], v[140:143], v[172:175], v[40:43]
	v_mfma_f32_16x16x32_bf16 v[28:31], v[132:135], v[180:183], v[28:31]
	v_mfma_f32_16x16x32_bf16 v[24:27], v[140:143], v[180:183], v[24:27]
	v_mfma_f32_16x16x32_bf16 v[12:15], v[132:135], v[188:191], v[12:15]
	v_mfma_f32_16x16x32_bf16 v[8:11], v[140:143], v[188:191], v[8:11]
	s_setprio 0
	s_setprio 1
	v_mfma_f32_16x16x32_bf16 v[52:55], v[144:147], v[160:163], v[52:55]
	v_mfma_f32_16x16x32_bf16 v[48:51], v[152:155], v[160:163], v[48:51]
	v_mfma_f32_16x16x32_bf16 v[36:39], v[144:147], v[168:171], v[36:39]
	v_mfma_f32_16x16x32_bf16 v[32:35], v[152:155], v[168:171], v[32:35]
	v_mfma_f32_16x16x32_bf16 v[20:23], v[144:147], v[176:179], v[20:23]
	v_mfma_f32_16x16x32_bf16 v[16:19], v[152:155], v[176:179], v[16:19]
	v_mfma_f32_16x16x32_bf16 v[4:7], v[144:147], v[184:187], v[4:7]
	v_mfma_f32_16x16x32_bf16 v[0:3], v[152:155], v[184:187], v[0:3]
	v_mfma_f32_16x16x32_bf16 v[52:55], v[148:151], v[164:167], v[52:55]
	v_mfma_f32_16x16x32_bf16 v[48:51], v[156:159], v[164:167], v[48:51]
	v_mfma_f32_16x16x32_bf16 v[36:39], v[148:151], v[172:175], v[36:39]
	v_mfma_f32_16x16x32_bf16 v[32:35], v[156:159], v[172:175], v[32:35]
	v_mfma_f32_16x16x32_bf16 v[20:23], v[148:151], v[180:183], v[20:23]
	v_mfma_f32_16x16x32_bf16 v[16:19], v[156:159], v[180:183], v[16:19]
	v_mfma_f32_16x16x32_bf16 v[4:7], v[148:151], v[188:191], v[4:7]
	v_mfma_f32_16x16x32_bf16 v[0:3], v[156:159], v[188:191], v[0:3]
	s_setprio 0
	s_barrier
	s_add_i32 s12, 0, 0x18000
	s_add_i32 s13, 0, 0x1c000
	v_add_u32_e32 v140, s12, v223
	v_add_u32_e32 v156, s13, v223
	ds_read_b128 v[128:131], v140
	ds_read_b128 v[132:135], v140 offset:1024
	ds_read_b128 v[136:139], v140 offset:2048
	ds_read_b128 v[140:143], v140 offset:3072
	ds_read_b128 v[144:147], v156
	ds_read_b128 v[148:151], v156 offset:1024
	ds_read_b128 v[152:155], v156 offset:2048
	ds_read_b128 v[156:159], v156 offset:3072
	s_add_u32 s42, s42, 0x100000
	s_addc_u32 s43, s43, 0
	s_mov_b32 m0, s6
	v_lshl_add_u64 v[214:215], s[42:43], 0, v[204:205]
	ds_read_b128 v[160:163], v224 offset:32768
	ds_read_b128 v[164:167], v224 offset:33792
	ds_read_b128 v[168:171], v224 offset:34816
	ds_read_b128 v[172:175], v224 offset:35840
	ds_read_b128 v[176:179], v224 offset:36864
	ds_read_b128 v[180:183], v224 offset:37888
	ds_read_b128 v[184:187], v224 offset:38912
	ds_read_b128 v[188:191], v224 offset:39936
	global_load_lds_dwordx4 v[214:215], off
	v_lshl_add_u64 v[214:215], s[42:43], 0, v[200:201]
	s_mov_b32 m0, s7
	s_nop 0
	global_load_lds_dwordx4 v[214:215], off
	s_waitcnt vmcnt(8)
	s_waitcnt lgkmcnt(0)
	s_barrier
	s_setprio 1
	v_mfma_f32_16x16x32_bf16 v[124:127], v[128:131], v[160:163], v[124:127]
	v_mfma_f32_16x16x32_bf16 v[120:123], v[136:139], v[160:163], v[120:123]
	v_mfma_f32_16x16x32_bf16 v[108:111], v[128:131], v[168:171], v[108:111]
	v_mfma_f32_16x16x32_bf16 v[104:107], v[136:139], v[168:171], v[104:107]
	v_mfma_f32_16x16x32_bf16 v[92:95], v[128:131], v[176:179], v[92:95]
	v_mfma_f32_16x16x32_bf16 v[88:91], v[136:139], v[176:179], v[88:91]
	v_mfma_f32_16x16x32_bf16 v[76:79], v[128:131], v[184:187], v[76:79]
	v_mfma_f32_16x16x32_bf16 v[72:75], v[136:139], v[184:187], v[72:75]
	v_mfma_f32_16x16x32_bf16 v[124:127], v[132:135], v[164:167], v[124:127]
	v_mfma_f32_16x16x32_bf16 v[120:123], v[140:143], v[164:167], v[120:123]
	v_mfma_f32_16x16x32_bf16 v[108:111], v[132:135], v[172:175], v[108:111]
	v_mfma_f32_16x16x32_bf16 v[104:107], v[140:143], v[172:175], v[104:107]
	v_mfma_f32_16x16x32_bf16 v[92:95], v[132:135], v[180:183], v[92:95]
	v_mfma_f32_16x16x32_bf16 v[88:91], v[140:143], v[180:183], v[88:91]
	v_mfma_f32_16x16x32_bf16 v[76:79], v[132:135], v[188:191], v[76:79]
	v_mfma_f32_16x16x32_bf16 v[72:75], v[140:143], v[188:191], v[72:75]
	s_setprio 0
	s_setprio 1
	v_mfma_f32_16x16x32_bf16 v[116:119], v[144:147], v[160:163], v[116:119]
	v_mfma_f32_16x16x32_bf16 v[112:115], v[152:155], v[160:163], v[112:115]
	v_mfma_f32_16x16x32_bf16 v[100:103], v[144:147], v[168:171], v[100:103]
	v_mfma_f32_16x16x32_bf16 v[96:99], v[152:155], v[168:171], v[96:99]
	v_mfma_f32_16x16x32_bf16 v[84:87], v[144:147], v[176:179], v[84:87]
	v_mfma_f32_16x16x32_bf16 v[80:83], v[152:155], v[176:179], v[80:83]
	v_mfma_f32_16x16x32_bf16 v[68:71], v[144:147], v[184:187], v[68:71]
	v_mfma_f32_16x16x32_bf16 v[64:67], v[152:155], v[184:187], v[64:67]
	v_mfma_f32_16x16x32_bf16 v[116:119], v[148:151], v[164:167], v[116:119]
	v_mfma_f32_16x16x32_bf16 v[112:115], v[156:159], v[164:167], v[112:115]
	v_mfma_f32_16x16x32_bf16 v[100:103], v[148:151], v[172:175], v[100:103]
	v_mfma_f32_16x16x32_bf16 v[96:99], v[156:159], v[172:175], v[96:99]
	v_mfma_f32_16x16x32_bf16 v[84:87], v[148:151], v[180:183], v[84:87]
	v_mfma_f32_16x16x32_bf16 v[80:83], v[156:159], v[180:183], v[80:83]
	v_mfma_f32_16x16x32_bf16 v[68:71], v[148:151], v[188:191], v[68:71]
	v_mfma_f32_16x16x32_bf16 v[64:67], v[156:159], v[188:191], v[64:67]
	s_setprio 0
	s_barrier
	s_add_i32 s12, s12, s0
	v_lshl_add_u64 v[194:195], v[194:195], 0, s[34:35]
	s_mov_b32 m0, s12
	ds_read_b128 v[160:163], v224 offset:49152
	ds_read_b128 v[164:167], v224 offset:50176
	ds_read_b128 v[168:171], v224 offset:51200
	ds_read_b128 v[172:175], v224 offset:52224
	ds_read_b128 v[176:179], v224 offset:53248
	ds_read_b128 v[180:183], v224 offset:54272
	ds_read_b128 v[184:187], v224 offset:55296
	ds_read_b128 v[188:191], v224 offset:56320
	global_load_lds_dwordx4 v[194:195], off
	s_add_i32 m0, s12, 0x2000
	s_add_u32 s24, s24, 0x100080
	v_lshl_add_u64 v[194:195], v[196:197], 0, s[34:35]
	s_addc_u32 s25, s25, 0
	s_add_i32 s12, s13, s0
	global_load_lds_dwordx4 v[194:195], off
	v_lshl_add_u64 v[194:195], s[24:25], 0, v[202:203]
	s_mov_b32 m0, s12
	s_nop 0
	global_load_lds_dwordx4 v[194:195], off
	v_lshl_add_u64 v[194:195], s[24:25], 0, v[198:199]
	s_add_i32 m0, s12, 0x2000
	s_nop 0
	global_load_lds_dwordx4 v[194:195], off
	v_lshl_add_u64 v[194:195], v[210:211], 0, s[34:35]
	s_mov_b32 m0, s44
	s_nop 0
	global_load_lds_dwordx4 v[194:195], off
	v_lshl_add_u64 v[194:195], v[212:213], 0, s[34:35]
	s_mov_b32 m0, s45
	s_nop 0
	global_load_lds_dwordx4 v[194:195], off
	s_waitcnt vmcnt(8)
	s_waitcnt lgkmcnt(0)
	s_barrier
	s_setprio 1
	v_mfma_f32_16x16x32_bf16 v[60:63], v[128:131], v[160:163], v[60:63]
	v_mfma_f32_16x16x32_bf16 v[56:59], v[136:139], v[160:163], v[56:59]
	v_mfma_f32_16x16x32_bf16 v[44:47], v[128:131], v[168:171], v[44:47]
	v_mfma_f32_16x16x32_bf16 v[40:43], v[136:139], v[168:171], v[40:43]
	v_mfma_f32_16x16x32_bf16 v[28:31], v[128:131], v[176:179], v[28:31]
	v_mfma_f32_16x16x32_bf16 v[24:27], v[136:139], v[176:179], v[24:27]
	v_mfma_f32_16x16x32_bf16 v[12:15], v[128:131], v[184:187], v[12:15]
	v_mfma_f32_16x16x32_bf16 v[8:11], v[136:139], v[184:187], v[8:11]
	v_mfma_f32_16x16x32_bf16 v[60:63], v[132:135], v[164:167], v[60:63]
	v_mfma_f32_16x16x32_bf16 v[56:59], v[140:143], v[164:167], v[56:59]
	v_mfma_f32_16x16x32_bf16 v[44:47], v[132:135], v[172:175], v[44:47]
	v_mfma_f32_16x16x32_bf16 v[40:43], v[140:143], v[172:175], v[40:43]
	v_mfma_f32_16x16x32_bf16 v[28:31], v[132:135], v[180:183], v[28:31]
	v_mfma_f32_16x16x32_bf16 v[24:27], v[140:143], v[180:183], v[24:27]
	v_mfma_f32_16x16x32_bf16 v[12:15], v[132:135], v[188:191], v[12:15]
	v_mfma_f32_16x16x32_bf16 v[8:11], v[140:143], v[188:191], v[8:11]
	s_setprio 0
	s_setprio 1
	v_mfma_f32_16x16x32_bf16 v[52:55], v[144:147], v[160:163], v[52:55]
	v_mfma_f32_16x16x32_bf16 v[48:51], v[152:155], v[160:163], v[48:51]
	v_mfma_f32_16x16x32_bf16 v[36:39], v[144:147], v[168:171], v[36:39]
	v_mfma_f32_16x16x32_bf16 v[32:35], v[152:155], v[168:171], v[32:35]
	v_mfma_f32_16x16x32_bf16 v[20:23], v[144:147], v[176:179], v[20:23]
	v_mfma_f32_16x16x32_bf16 v[16:19], v[152:155], v[176:179], v[16:19]
	v_mfma_f32_16x16x32_bf16 v[4:7], v[144:147], v[184:187], v[4:7]
	v_mfma_f32_16x16x32_bf16 v[0:3], v[152:155], v[184:187], v[0:3]
	v_mfma_f32_16x16x32_bf16 v[52:55], v[148:151], v[164:167], v[52:55]
	v_mfma_f32_16x16x32_bf16 v[48:51], v[156:159], v[164:167], v[48:51]
	v_mfma_f32_16x16x32_bf16 v[36:39], v[148:151], v[172:175], v[36:39]
	v_mfma_f32_16x16x32_bf16 v[32:35], v[156:159], v[172:175], v[32:35]
	v_mfma_f32_16x16x32_bf16 v[20:23], v[148:151], v[180:183], v[20:23]
	v_mfma_f32_16x16x32_bf16 v[16:19], v[156:159], v[180:183], v[16:19]
	v_mfma_f32_16x16x32_bf16 v[4:7], v[148:151], v[188:191], v[4:7]
	v_mfma_f32_16x16x32_bf16 v[0:3], v[156:159], v[188:191], v[0:3]
	s_setprio 0
	s_barrier
	s_add_i32 s75, s75, 2
	s_add_u32 s40, s40, 0x100
	s_addc_u32 s41, s41, 0
	s_add_u32 s73, s73, 0x100
	s_addc_u32 s74, s74, 0
	s_cmp_lt_u32 s75, 62
	s_cbranch_scc1 .LBB0_196
	s_andn2_b64 vcc, exec, s[46:47]
	s_cbranch_vccnz .LBB0_199
	s_barrier

.LBB0_461:
	s_add_u32 s12, s56, 0xfff00080
	s_addc_u32 s13, s57, -1
	s_add_i32 s74, 0, 0x10000
	s_cmp_eq_u32 s73, 60
	s_cselect_b32 s61, s47, s13
	s_cselect_b32 s60, s59, s12
	v_add_u32_e32 v138, s74, v140
	s_cselect_b32 s25, s43, s72
	s_cselect_b32 s24, s62, s63
	s_add_i32 s12, 0, 0x14000
	ds_read_b128 v[142:145], v138
	ds_read_b128 v[146:149], v138 offset:1024
	ds_read_b128 v[150:153], v138 offset:2048
	ds_read_b128 v[154:157], v138 offset:3072
	v_add_u32_e32 v138, s12, v140
	ds_read_b128 v[158:161], v138
	ds_read_b128 v[162:165], v138 offset:1024
	ds_read_b128 v[166:169], v138 offset:2048
	ds_read_b128 v[170:173], v138 offset:3072
	v_lshl_add_u64 v[138:139], s[56:57], 0, v[134:135]
	s_add_i32 m0, s4, 0xc000
	ds_read_b128 v[174:177], v141
	ds_read_b128 v[178:181], v141 offset:1024
	ds_read_b128 v[182:185], v141 offset:2048
	ds_read_b128 v[186:189], v141 offset:3072
	ds_read_b128 v[194:197], v141 offset:4096
	ds_read_b128 v[198:201], v141 offset:5120
	ds_read_b128 v[202:205], v141 offset:6144
	ds_read_b128 v[206:209], v141 offset:7168
	global_load_lds_dwordx4 v[138:139], off
	v_lshl_add_u64 v[138:139], s[56:57], 0, v[136:137]
	s_add_i32 m0, s4, 0xe000
	s_nop 0
	global_load_lds_dwordx4 v[138:139], off
	s_waitcnt vmcnt(8)
	s_waitcnt lgkmcnt(0)
	s_barrier
	s_setprio 1
	v_mfma_f32_16x16x32_bf16 v[124:127], v[142:145], v[174:177], v[124:127]
	v_mfma_f32_16x16x32_bf16 v[120:123], v[150:153], v[174:177], v[120:123]
	v_mfma_f32_16x16x32_bf16 v[116:119], v[142:145], v[182:185], v[116:119]
	v_mfma_f32_16x16x32_bf16 v[108:111], v[150:153], v[182:185], v[108:111]
	v_mfma_f32_16x16x32_bf16 v[100:103], v[142:145], v[194:197], v[100:103]
	v_mfma_f32_16x16x32_bf16 v[92:95], v[150:153], v[194:197], v[92:95]
	v_mfma_f32_16x16x32_bf16 v[84:87], v[142:145], v[202:205], v[84:87]
	v_mfma_f32_16x16x32_bf16 v[76:79], v[150:153], v[202:205], v[76:79]
	v_mfma_f32_16x16x32_bf16 v[124:127], v[146:149], v[178:181], v[124:127]
	v_mfma_f32_16x16x32_bf16 v[120:123], v[154:157], v[178:181], v[120:123]
	v_mfma_f32_16x16x32_bf16 v[116:119], v[146:149], v[186:189], v[116:119]
	v_mfma_f32_16x16x32_bf16 v[108:111], v[154:157], v[186:189], v[108:111]
	v_mfma_f32_16x16x32_bf16 v[100:103], v[146:149], v[198:201], v[100:103]
	v_mfma_f32_16x16x32_bf16 v[92:95], v[154:157], v[198:201], v[92:95]
	v_mfma_f32_16x16x32_bf16 v[84:87], v[146:149], v[206:209], v[84:87]
	v_mfma_f32_16x16x32_bf16 v[76:79], v[154:157], v[206:209], v[76:79]
	s_setprio 0
	s_setprio 1
	v_mfma_f32_16x16x32_bf16 v[112:115], v[158:161], v[174:177], v[112:115]
	v_mfma_f32_16x16x32_bf16 v[104:107], v[166:169], v[174:177], v[104:107]
	v_mfma_f32_16x16x32_bf16 v[96:99], v[158:161], v[182:185], v[96:99]
	v_mfma_f32_16x16x32_bf16 v[88:91], v[166:169], v[182:185], v[88:91]
	v_mfma_f32_16x16x32_bf16 v[80:83], v[158:161], v[194:197], v[80:83]
	v_mfma_f32_16x16x32_bf16 v[72:75], v[166:169], v[194:197], v[72:75]
	v_mfma_f32_16x16x32_bf16 v[68:71], v[158:161], v[202:205], v[68:71]
	v_mfma_f32_16x16x32_bf16 v[64:67], v[166:169], v[202:205], v[64:67]
	v_mfma_f32_16x16x32_bf16 v[112:115], v[162:165], v[178:181], v[112:115]
	v_mfma_f32_16x16x32_bf16 v[104:107], v[170:173], v[178:181], v[104:107]
	v_mfma_f32_16x16x32_bf16 v[96:99], v[162:165], v[186:189], v[96:99]
	v_mfma_f32_16x16x32_bf16 v[88:91], v[170:173], v[186:189], v[88:91]
	v_mfma_f32_16x16x32_bf16 v[80:83], v[162:165], v[198:201], v[80:83]
	v_mfma_f32_16x16x32_bf16 v[72:75], v[170:173], v[198:201], v[72:75]
	v_mfma_f32_16x16x32_bf16 v[68:71], v[162:165], v[206:209], v[68:71]
	v_mfma_f32_16x16x32_bf16 v[64:67], v[170:173], v[206:209], v[64:67]
	s_setprio 0
	s_barrier
	s_add_i32 s13, s74, s0
	v_lshl_add_u64 v[138:139], s[24:25], 0, v[192:193]
	s_mov_b32 m0, s13
	ds_read_b128 v[174:177], v141 offset:16384
	ds_read_b128 v[178:181], v141 offset:17408
	ds_read_b128 v[182:185], v141 offset:18432
	ds_read_b128 v[186:189], v141 offset:19456
	ds_read_b128 v[194:197], v141 offset:20480
	ds_read_b128 v[198:201], v141 offset:21504
	ds_read_b128 v[202:205], v141 offset:22528
	ds_read_b128 v[206:209], v141 offset:23552
	global_load_lds_dwordx4 v[138:139], off
	s_add_i32 m0, s13, 0x2000
	s_add_u32 s74, s24, 0x100000
	v_lshl_add_u64 v[190:191], s[24:25], 0, v[128:129]
	s_addc_u32 s75, s25, 0
	s_add_i32 s12, s12, s0
	global_load_lds_dwordx4 v[190:191], off
	v_lshl_add_u64 v[210:211], s[74:75], 0, v[192:193]
	s_mov_b32 m0, s12
	v_lshl_add_u64 v[212:213], s[60:61], 0, v[130:131]
	global_load_lds_dwordx4 v[210:211], off
	v_lshl_add_u64 v[210:211], s[74:75], 0, v[128:129]
	s_add_i32 m0, s12, 0x2000
	s_nop 0
	global_load_lds_dwordx4 v[210:211], off
	v_lshl_add_u64 v[210:211], s[60:61], 0, v[132:133]
	s_mov_b32 m0, s4
	s_nop 0
	global_load_lds_dwordx4 v[210:211], off
	s_mov_b32 m0, s5
	s_nop 0
	global_load_lds_dwordx4 v[212:213], off
	s_waitcnt vmcnt(8)
	s_waitcnt lgkmcnt(0)
	s_barrier
	s_setprio 1
	v_mfma_f32_16x16x32_bf16 v[60:63], v[142:145], v[174:177], v[60:63]
	v_mfma_f32_16x16x32_bf16 v[56:59], v[150:153], v[174:177], v[56:59]
	v_mfma_f32_16x16x32_bf16 v[52:55], v[142:145], v[182:185], v[52:55]
	v_mfma_f32_16x16x32_bf16 v[44:47], v[150:153], v[182:185], v[44:47]
	v_mfma_f32_16x16x32_bf16 v[36:39], v[142:145], v[194:197], v[36:39]
	v_mfma_f32_16x16x32_bf16 v[28:31], v[150:153], v[194:197], v[28:31]
	v_mfma_f32_16x16x32_bf16 v[20:23], v[142:145], v[202:205], v[20:23]
	v_mfma_f32_16x16x32_bf16 v[12:15], v[150:153], v[202:205], v[12:15]
	v_mfma_f32_16x16x32_bf16 v[60:63], v[146:149], v[178:181], v[60:63]
	v_mfma_f32_16x16x32_bf16 v[56:59], v[154:157], v[178:181], v[56:59]
	v_mfma_f32_16x16x32_bf16 v[52:55], v[146:149], v[186:189], v[52:55]
	v_mfma_f32_16x16x32_bf16 v[44:47], v[154:157], v[186:189], v[44:47]
	v_mfma_f32_16x16x32_bf16 v[36:39], v[146:149], v[198:201], v[36:39]
	v_mfma_f32_16x16x32_bf16 v[28:31], v[154:157], v[198:201], v[28:31]
	v_mfma_f32_16x16x32_bf16 v[20:23], v[146:149], v[206:209], v[20:23]
	v_mfma_f32_16x16x32_bf16 v[12:15], v[154:157], v[206:209], v[12:15]
	s_setprio 0
	s_setprio 1
	v_mfma_f32_16x16x32_bf16 v[48:51], v[158:161], v[174:177], v[48:51]
	v_mfma_f32_16x16x32_bf16 v[40:43], v[166:169], v[174:177], v[40:43]
	v_mfma_f32_16x16x32_bf16 v[32:35], v[158:161], v[182:185], v[32:35]
	v_mfma_f32_16x16x32_bf16 v[24:27], v[166:169], v[182:185], v[24:27]
	v_mfma_f32_16x16x32_bf16 v[16:19], v[158:161], v[194:197], v[16:19]
	v_mfma_f32_16x16x32_bf16 v[8:11], v[166:169], v[194:197], v[8:11]
	v_mfma_f32_16x16x32_bf16 v[4:7], v[158:161], v[202:205], v[4:7]
	v_mfma_f32_16x16x32_bf16 v[0:3], v[166:169], v[202:205], v[0:3]
	v_mfma_f32_16x16x32_bf16 v[48:51], v[162:165], v[178:181], v[48:51]
	v_mfma_f32_16x16x32_bf16 v[40:43], v[170:173], v[178:181], v[40:43]
	v_mfma_f32_16x16x32_bf16 v[32:35], v[162:165], v[186:189], v[32:35]
	v_mfma_f32_16x16x32_bf16 v[24:27], v[170:173], v[186:189], v[24:27]
	v_mfma_f32_16x16x32_bf16 v[16:19], v[162:165], v[198:201], v[16:19]
	v_mfma_f32_16x16x32_bf16 v[8:11], v[170:173], v[198:201], v[8:11]
	v_mfma_f32_16x16x32_bf16 v[4:7], v[162:165], v[206:209], v[4:7]
	v_mfma_f32_16x16x32_bf16 v[0:3], v[170:173], v[206:209], v[0:3]
	s_setprio 0
	s_barrier
	s_add_i32 s12, 0, 0x18000
	s_add_i32 s13, 0, 0x1c000
	v_add_u32_e32 v154, s12, v140
	v_add_u32_e32 v170, s13, v140
	ds_read_b128 v[142:145], v154
	ds_read_b128 v[146:149], v154 offset:1024
	ds_read_b128 v[150:153], v154 offset:2048
	ds_read_b128 v[154:157], v154 offset:3072
	ds_read_b128 v[158:161], v170
	ds_read_b128 v[162:165], v170 offset:1024
	ds_read_b128 v[166:169], v170 offset:2048
	ds_read_b128 v[170:173], v170 offset:3072
	s_add_u32 s60, s60, 0x100000
	s_addc_u32 s61, s61, 0
	s_mov_b32 m0, s6
	v_lshl_add_u64 v[214:215], s[60:61], 0, v[132:133]
	ds_read_b128 v[174:177], v141 offset:32768
	ds_read_b128 v[178:181], v141 offset:33792
	ds_read_b128 v[182:185], v141 offset:34816
	ds_read_b128 v[186:189], v141 offset:35840
	ds_read_b128 v[194:197], v141 offset:36864
	ds_read_b128 v[198:201], v141 offset:37888
	ds_read_b128 v[202:205], v141 offset:38912
	ds_read_b128 v[206:209], v141 offset:39936
	global_load_lds_dwordx4 v[214:215], off
	v_lshl_add_u64 v[214:215], s[60:61], 0, v[130:131]
	s_mov_b32 m0, s7
	s_nop 0
	global_load_lds_dwordx4 v[214:215], off
	s_waitcnt vmcnt(8)
	s_waitcnt lgkmcnt(0)
	s_barrier
	s_setprio 1
	v_mfma_f32_16x16x32_bf16 v[124:127], v[142:145], v[174:177], v[124:127]
	v_mfma_f32_16x16x32_bf16 v[120:123], v[150:153], v[174:177], v[120:123]
	v_mfma_f32_16x16x32_bf16 v[116:119], v[142:145], v[182:185], v[116:119]
	v_mfma_f32_16x16x32_bf16 v[108:111], v[150:153], v[182:185], v[108:111]
	v_mfma_f32_16x16x32_bf16 v[100:103], v[142:145], v[194:197], v[100:103]
	v_mfma_f32_16x16x32_bf16 v[92:95], v[150:153], v[194:197], v[92:95]
	v_mfma_f32_16x16x32_bf16 v[84:87], v[142:145], v[202:205], v[84:87]
	v_mfma_f32_16x16x32_bf16 v[76:79], v[150:153], v[202:205], v[76:79]
	v_mfma_f32_16x16x32_bf16 v[124:127], v[146:149], v[178:181], v[124:127]
	v_mfma_f32_16x16x32_bf16 v[120:123], v[154:157], v[178:181], v[120:123]
	v_mfma_f32_16x16x32_bf16 v[116:119], v[146:149], v[186:189], v[116:119]
	v_mfma_f32_16x16x32_bf16 v[108:111], v[154:157], v[186:189], v[108:111]
	v_mfma_f32_16x16x32_bf16 v[100:103], v[146:149], v[198:201], v[100:103]
	v_mfma_f32_16x16x32_bf16 v[92:95], v[154:157], v[198:201], v[92:95]
	v_mfma_f32_16x16x32_bf16 v[84:87], v[146:149], v[206:209], v[84:87]
	v_mfma_f32_16x16x32_bf16 v[76:79], v[154:157], v[206:209], v[76:79]
	s_setprio 0
	s_setprio 1
	v_mfma_f32_16x16x32_bf16 v[112:115], v[158:161], v[174:177], v[112:115]
	v_mfma_f32_16x16x32_bf16 v[104:107], v[166:169], v[174:177], v[104:107]
	v_mfma_f32_16x16x32_bf16 v[96:99], v[158:161], v[182:185], v[96:99]
	v_mfma_f32_16x16x32_bf16 v[88:91], v[166:169], v[182:185], v[88:91]
	v_mfma_f32_16x16x32_bf16 v[80:83], v[158:161], v[194:197], v[80:83]
	v_mfma_f32_16x16x32_bf16 v[72:75], v[166:169], v[194:197], v[72:75]
	v_mfma_f32_16x16x32_bf16 v[68:71], v[158:161], v[202:205], v[68:71]
	v_mfma_f32_16x16x32_bf16 v[64:67], v[166:169], v[202:205], v[64:67]
	v_mfma_f32_16x16x32_bf16 v[112:115], v[162:165], v[178:181], v[112:115]
	v_mfma_f32_16x16x32_bf16 v[104:107], v[170:173], v[178:181], v[104:107]
	v_mfma_f32_16x16x32_bf16 v[96:99], v[162:165], v[186:189], v[96:99]
	v_mfma_f32_16x16x32_bf16 v[88:91], v[170:173], v[186:189], v[88:91]
	v_mfma_f32_16x16x32_bf16 v[80:83], v[162:165], v[198:201], v[80:83]
	v_mfma_f32_16x16x32_bf16 v[72:75], v[170:173], v[198:201], v[72:75]
	v_mfma_f32_16x16x32_bf16 v[68:71], v[162:165], v[206:209], v[68:71]
	v_mfma_f32_16x16x32_bf16 v[64:67], v[170:173], v[206:209], v[64:67]
	s_setprio 0
	s_barrier
; #define PG8_MMA(ai, bj, At, Bt) do { __builtin_amdgcn_s_setprio(1); _Pragma("unroll") for (int m = 0; m < 4; ++m) _Pragma("unroll") for (int n = 0; n < 2; ++n) _Pragma("unroll") for (int k = 0; k < 2; ++k) \
;         acc[ai][bj][m][n] = __builtin_amdgcn_mfma_f32_16x16x32_bf16(Bt[n][k], At[m][k], acc[ai][bj][m][n], 0, 0, 0); __builtin_amdgcn_s_setprio(0); } while (0)
; #define PG8_ITER_HEAD() \
;             const bool last = (t == nt - 2); \
;             const char* a1 = cA + (size_t)(t + 1) * kstep; \
;             const char* a2 = last ? nA : cA + (size_t)(t + 2) * kstep; const char* b2 = last ? nB : cB + (size_t)(t + 2) * kstep; \
;             const char* a3 = a2 + kstep; const char* b3 = b2 + kstep; \
;             if (last && has_next) S.a_ready(nxt);
;     ...
;         for (; t < nt; t += 2) {
;             PG8_ITER_HEAD()
;             if constexpr (SP2) {
;             PG8_ITER_SP2(PG8_MMA)
	s_add_i32 s12, s12, s0
	v_lshl_add_u64 v[138:139], v[138:139], 0, s[34:35]
	s_mov_b32 m0, s12
	ds_read_b128 v[174:177], v141 offset:49152
	ds_read_b128 v[178:181], v141 offset:50176
	ds_read_b128 v[182:185], v141 offset:51200
	ds_read_b128 v[186:189], v141 offset:52224
	ds_read_b128 v[194:197], v141 offset:53248
	ds_read_b128 v[198:201], v141 offset:54272
	ds_read_b128 v[202:205], v141 offset:55296
	ds_read_b128 v[206:209], v141 offset:56320
	global_load_lds_dwordx4 v[138:139], off
	s_add_i32 m0, s12, 0x2000
	s_add_u32 s24, s24, 0x100080
	v_lshl_add_u64 v[138:139], v[190:191], 0, s[34:35]
	s_addc_u32 s25, s25, 0
	s_add_i32 s12, s13, s0
	global_load_lds_dwordx4 v[138:139], off
	v_lshl_add_u64 v[138:139], s[24:25], 0, v[192:193]
	s_mov_b32 m0, s12
	s_nop 0
	global_load_lds_dwordx4 v[138:139], off
	v_lshl_add_u64 v[138:139], s[24:25], 0, v[128:129]
	s_add_i32 m0, s12, 0x2000
	s_nop 0
	global_load_lds_dwordx4 v[138:139], off
	v_lshl_add_u64 v[138:139], v[210:211], 0, s[34:35]
	s_mov_b32 m0, s10
	s_nop 0
	global_load_lds_dwordx4 v[138:139], off
	v_lshl_add_u64 v[138:139], v[212:213], 0, s[34:35]
	s_mov_b32 m0, s11
	s_nop 0
	global_load_lds_dwordx4 v[138:139], off
	s_waitcnt vmcnt(8)
	s_waitcnt lgkmcnt(0)
	s_barrier
	s_setprio 1
	v_mfma_f32_16x16x32_bf16 v[60:63], v[142:145], v[174:177], v[60:63]
	v_mfma_f32_16x16x32_bf16 v[56:59], v[150:153], v[174:177], v[56:59]
	v_mfma_f32_16x16x32_bf16 v[52:55], v[142:145], v[182:185], v[52:55]
	v_mfma_f32_16x16x32_bf16 v[44:47], v[150:153], v[182:185], v[44:47]
	v_mfma_f32_16x16x32_bf16 v[36:39], v[142:145], v[194:197], v[36:39]
	v_mfma_f32_16x16x32_bf16 v[28:31], v[150:153], v[194:197], v[28:31]
	v_mfma_f32_16x16x32_bf16 v[20:23], v[142:145], v[202:205], v[20:23]
	v_mfma_f32_16x16x32_bf16 v[12:15], v[150:153], v[202:205], v[12:15]
	v_mfma_f32_16x16x32_bf16 v[60:63], v[146:149], v[178:181], v[60:63]
	v_mfma_f32_16x16x32_bf16 v[56:59], v[154:157], v[178:181], v[56:59]
	v_mfma_f32_16x16x32_bf16 v[52:55], v[146:149], v[186:189], v[52:55]
	v_mfma_f32_16x16x32_bf16 v[44:47], v[154:157], v[186:189], v[44:47]
	v_mfma_f32_16x16x32_bf16 v[36:39], v[146:149], v[198:201], v[36:39]
	v_mfma_f32_16x16x32_bf16 v[28:31], v[154:157], v[198:201], v[28:31]
	v_mfma_f32_16x16x32_bf16 v[20:23], v[146:149], v[206:209], v[20:23]
	v_mfma_f32_16x16x32_bf16 v[12:15], v[154:157], v[206:209], v[12:15]
	s_setprio 0
	s_setprio 1
	v_mfma_f32_16x16x32_bf16 v[48:51], v[158:161], v[174:177], v[48:51]
	v_mfma_f32_16x16x32_bf16 v[40:43], v[166:169], v[174:177], v[40:43]
	v_mfma_f32_16x16x32_bf16 v[32:35], v[158:161], v[182:185], v[32:35]
	v_mfma_f32_16x16x32_bf16 v[24:27], v[166:169], v[182:185], v[24:27]
	v_mfma_f32_16x16x32_bf16 v[16:19], v[158:161], v[194:197], v[16:19]
	v_mfma_f32_16x16x32_bf16 v[8:11], v[166:169], v[194:197], v[8:11]
	v_mfma_f32_16x16x32_bf16 v[4:7], v[158:161], v[202:205], v[4:7]
	v_mfma_f32_16x16x32_bf16 v[0:3], v[166:169], v[202:205], v[0:3]
	v_mfma_f32_16x16x32_bf16 v[48:51], v[162:165], v[178:181], v[48:51]
	v_mfma_f32_16x16x32_bf16 v[40:43], v[170:173], v[178:181], v[40:43]
	v_mfma_f32_16x16x32_bf16 v[32:35], v[162:165], v[186:189], v[32:35]
	v_mfma_f32_16x16x32_bf16 v[24:27], v[170:173], v[186:189], v[24:27]
	v_mfma_f32_16x16x32_bf16 v[16:19], v[162:165], v[198:201], v[16:19]
	v_mfma_f32_16x16x32_bf16 v[8:11], v[170:173], v[198:201], v[8:11]
	v_mfma_f32_16x16x32_bf16 v[4:7], v[162:165], v[206:209], v[4:7]
	v_mfma_f32_16x16x32_bf16 v[0:3], v[170:173], v[206:209], v[0:3]
	s_setprio 0
	s_barrier
	s_add_i32 s73, s73, 2
	s_add_u32 s56, s56, 0x100
	s_addc_u32 s57, s57, 0
	s_add_u32 s63, s63, 0x100
	s_addc_u32 s72, s72, 0
	s_cmp_lt_u32 s73, 62
	s_cbranch_scc1 .LBB0_461
	s_andn2_b64 vcc, exec, s[38:39]
	s_cbranch_vccnz .LBB0_464
	s_barrier

; #define PG8_ITER_HEAD() \
;             const bool last = (t == nt - 2); \
;             const char* a1 = cA + (size_t)(t + 1) * kstep; \
;             const char* a2 = last ? nA : cA + (size_t)(t + 2) * kstep; const char* b2 = last ? nB : cB + (size_t)(t + 2) * kstep; \
;             const char* a3 = a2 + kstep; const char* b3 = b2 + kstep; \
;             if (last && has_next) S.a_ready(nxt);
;     ...
;             for (; t < nt; t += 2) { PG8_ITER_HEAD() PG8_ITER_SP2(PG8_MMAI) }
.LBB0_552:
	s_add_u32 s12, s50, 0xfff80080
	s_addc_u32 s13, s51, -1
	s_add_i32 s44, 0, 0x10000
	s_cmp_eq_u32 s29, 28
	s_cselect_b32 s53, s6, s13
	s_cselect_b32 s52, s7, s12
	s_cselect_b32 s25, s8, s11
	s_cselect_b32 s24, s9, s10
	s_add_i32 s12, 0, 0x14000
	s_waitcnt vmcnt(0)
	v_add_u32_e32 v60, s44, v198
	v_add_u32_e32 v166, s12, v198
	ds_read_b128 v[20:23], v60
	ds_read_b128 v[32:35], v60 offset:1024
	ds_read_b128 v[56:59], v60 offset:2048
	ds_read_b128 v[60:63], v60 offset:3072
	ds_read_b128 v[154:157], v166
	ds_read_b128 v[158:161], v166 offset:1024
	ds_read_b128 v[162:165], v166 offset:2048
	ds_read_b128 v[166:169], v166 offset:3072
	v_lshl_add_u64 v[190:191], s[50:51], 0, v[150:151]
	s_add_i32 m0, s56, 0xc000
	ds_read_b128 v[170:173], v199
	ds_read_b128 v[174:177], v199 offset:1024
	ds_read_b128 v[178:181], v199 offset:2048
	ds_read_b128 v[182:185], v199 offset:3072
	ds_read_b128 v[186:189], v199 offset:4096
	ds_read_b128 v[194:197], v199 offset:5120
	ds_read_b128 v[200:203], v199 offset:6144
	ds_read_b128 v[204:207], v199 offset:7168
	global_load_lds_dwordx4 v[190:191], off
	v_lshl_add_u64 v[190:191], s[50:51], 0, v[152:153]
	s_add_i32 m0, s56, 0xe000
	s_nop 0
	global_load_lds_dwordx4 v[190:191], off
	s_waitcnt vmcnt(8)
	s_waitcnt lgkmcnt(0)
	s_barrier
	s_setprio 1
	v_mfma_i32_16x16x64_i8 v[140:143], v[20:23], v[170:173], v[140:143]
	v_mfma_i32_16x16x64_i8 v[136:139], v[56:59], v[170:173], v[136:139]
	v_mfma_i32_16x16x64_i8 v[132:135], v[20:23], v[178:181], v[132:135]
	v_mfma_i32_16x16x64_i8 v[124:127], v[56:59], v[178:181], v[124:127]
	v_mfma_i32_16x16x64_i8 v[116:119], v[20:23], v[186:189], v[116:119]
	v_mfma_i32_16x16x64_i8 v[108:111], v[56:59], v[186:189], v[108:111]
	v_mfma_i32_16x16x64_i8 v[100:103], v[20:23], v[200:203], v[100:103]
	v_mfma_i32_16x16x64_i8 v[92:95], v[56:59], v[200:203], v[92:95]
	v_mfma_i32_16x16x64_i8 v[140:143], v[32:35], v[174:177], v[140:143]
	v_mfma_i32_16x16x64_i8 v[136:139], v[60:63], v[174:177], v[136:139]
	v_mfma_i32_16x16x64_i8 v[132:135], v[32:35], v[182:185], v[132:135]
	v_mfma_i32_16x16x64_i8 v[124:127], v[60:63], v[182:185], v[124:127]
	v_mfma_i32_16x16x64_i8 v[116:119], v[32:35], v[194:197], v[116:119]
	v_mfma_i32_16x16x64_i8 v[108:111], v[60:63], v[194:197], v[108:111]
	v_mfma_i32_16x16x64_i8 v[100:103], v[32:35], v[204:207], v[100:103]
	v_mfma_i32_16x16x64_i8 v[92:95], v[60:63], v[204:207], v[92:95]
	s_setprio 0
	s_setprio 1
	v_mfma_i32_16x16x64_i8 v[128:131], v[154:157], v[170:173], v[128:131]
	v_mfma_i32_16x16x64_i8 v[120:123], v[162:165], v[170:173], v[120:123]
	v_mfma_i32_16x16x64_i8 v[112:115], v[154:157], v[178:181], v[112:115]
	v_mfma_i32_16x16x64_i8 v[104:107], v[162:165], v[178:181], v[104:107]
	v_mfma_i32_16x16x64_i8 v[96:99], v[154:157], v[186:189], v[96:99]
	v_mfma_i32_16x16x64_i8 v[88:91], v[162:165], v[186:189], v[88:91]
	v_mfma_i32_16x16x64_i8 v[84:87], v[154:157], v[200:203], v[84:87]
	v_mfma_i32_16x16x64_i8 v[80:83], v[162:165], v[200:203], v[80:83]
	v_mfma_i32_16x16x64_i8 v[128:131], v[158:161], v[174:177], v[128:131]
	v_mfma_i32_16x16x64_i8 v[120:123], v[166:169], v[174:177], v[120:123]
	v_mfma_i32_16x16x64_i8 v[112:115], v[158:161], v[182:185], v[112:115]
	v_mfma_i32_16x16x64_i8 v[104:107], v[166:169], v[182:185], v[104:107]
	v_mfma_i32_16x16x64_i8 v[96:99], v[158:161], v[194:197], v[96:99]
	v_mfma_i32_16x16x64_i8 v[88:91], v[166:169], v[194:197], v[88:91]
	v_mfma_i32_16x16x64_i8 v[84:87], v[158:161], v[204:207], v[84:87]
	v_mfma_i32_16x16x64_i8 v[80:83], v[166:169], v[204:207], v[80:83]
	s_setprio 0
	s_barrier
	s_add_i32 s13, s44, s0
	v_lshl_add_u64 v[190:191], s[24:25], 0, v[192:193]
	s_mov_b32 m0, s13
	ds_read_b128 v[170:173], v199 offset:16384
	ds_read_b128 v[174:177], v199 offset:17408
	ds_read_b128 v[178:181], v199 offset:18432
	ds_read_b128 v[182:185], v199 offset:19456
	ds_read_b128 v[186:189], v199 offset:20480
	ds_read_b128 v[194:197], v199 offset:21504
	ds_read_b128 v[200:203], v199 offset:22528
	ds_read_b128 v[204:207], v199 offset:23552
	global_load_lds_dwordx4 v[190:191], off
	s_add_i32 m0, s13, 0x2000
	s_add_u32 s44, s24, 0x80000
	v_lshl_add_u64 v[208:209], s[24:25], 0, v[144:145]
	s_addc_u32 s45, s25, 0
	s_add_i32 s12, s12, s0
	global_load_lds_dwordx4 v[208:209], off
	v_lshl_add_u64 v[210:211], s[44:45], 0, v[192:193]
	s_mov_b32 m0, s12
	v_lshl_add_u64 v[212:213], s[52:53], 0, v[146:147]
	global_load_lds_dwordx4 v[210:211], off
	v_lshl_add_u64 v[210:211], s[44:45], 0, v[144:145]
	s_add_i32 m0, s12, 0x2000
	s_nop 0
	global_load_lds_dwordx4 v[210:211], off
	v_lshl_add_u64 v[210:211], s[52:53], 0, v[148:149]
	s_mov_b32 m0, s56
	s_nop 0
	global_load_lds_dwordx4 v[210:211], off
	s_mov_b32 m0, s57
	s_nop 0
	global_load_lds_dwordx4 v[212:213], off
	s_waitcnt vmcnt(8)
	s_waitcnt lgkmcnt(0)
	s_barrier
	s_setprio 1
	v_mfma_i32_16x16x64_i8 v[76:79], v[20:23], v[170:173], v[76:79]
	v_mfma_i32_16x16x64_i8 v[72:75], v[56:59], v[170:173], v[72:75]
	v_mfma_i32_16x16x64_i8 v[52:55], v[20:23], v[178:181], v[52:55]
	v_mfma_i32_16x16x64_i8 v[44:47], v[56:59], v[178:181], v[44:47]
	v_mfma_i32_16x16x64_i8 v[36:39], v[20:23], v[186:189], v[36:39]
	v_mfma_i32_16x16x64_i8 v[24:27], v[56:59], v[186:189], v[24:27]
	v_mfma_i32_16x16x64_i8 v[12:15], v[20:23], v[200:203], v[12:15]
	v_mfma_i32_16x16x64_i8 v[4:7], v[56:59], v[200:203], v[4:7]
	v_mfma_i32_16x16x64_i8 v[76:79], v[32:35], v[174:177], v[76:79]
	v_mfma_i32_16x16x64_i8 v[72:75], v[60:63], v[174:177], v[72:75]
	v_mfma_i32_16x16x64_i8 v[52:55], v[32:35], v[182:185], v[52:55]
	v_mfma_i32_16x16x64_i8 v[44:47], v[60:63], v[182:185], v[44:47]
	v_mfma_i32_16x16x64_i8 v[36:39], v[32:35], v[194:197], v[36:39]
	v_mfma_i32_16x16x64_i8 v[24:27], v[60:63], v[194:197], v[24:27]
	v_mfma_i32_16x16x64_i8 v[12:15], v[32:35], v[204:207], v[12:15]
	v_mfma_i32_16x16x64_i8 v[4:7], v[60:63], v[204:207], v[4:7]
	s_setprio 0
	s_setprio 1
	v_mfma_i32_16x16x64_i8 v[48:51], v[154:157], v[178:181], v[48:51]
	v_mfma_i32_16x16x64_i8 v[40:43], v[162:165], v[178:181], v[40:43]
	v_mfma_i32_16x16x64_i8 v[28:31], v[154:157], v[186:189], v[28:31]
	v_mfma_i32_16x16x64_i8 v[16:19], v[162:165], v[186:189], v[16:19]
	v_mfma_i32_16x16x64_i8 v[8:11], v[154:157], v[200:203], v[8:11]
	v_mfma_i32_16x16x64_i8 v[0:3], v[162:165], v[200:203], v[0:3]
	v_mfma_i32_16x16x64_i8 v[20:23], v[154:157], v[170:173], v[68:71]
	v_mfma_i32_16x16x64_i8 v[32:35], v[162:165], v[170:173], v[64:67]
	v_mfma_i32_16x16x64_i8 v[48:51], v[158:161], v[182:185], v[48:51]
	v_mfma_i32_16x16x64_i8 v[40:43], v[166:169], v[182:185], v[40:43]
	v_mfma_i32_16x16x64_i8 v[28:31], v[158:161], v[194:197], v[28:31]
	v_mfma_i32_16x16x64_i8 v[16:19], v[166:169], v[194:197], v[16:19]
	v_mfma_i32_16x16x64_i8 v[8:11], v[158:161], v[204:207], v[8:11]
	v_mfma_i32_16x16x64_i8 v[0:3], v[166:169], v[204:207], v[0:3]
	v_mfma_i32_16x16x64_i8 v[20:23], v[158:161], v[174:177], v[20:23]
	v_mfma_i32_16x16x64_i8 v[32:35], v[166:169], v[174:177], v[32:35]
	s_setprio 0
	s_barrier
	s_add_i32 s12, 0, 0x18000
	s_add_i32 s13, 0, 0x1c000
	v_add_u32_e32 v68, s12, v198
	v_add_u32_e32 v166, s13, v198
	ds_read_b128 v[56:59], v68
	ds_read_b128 v[60:63], v68 offset:1024
	ds_read_b128 v[64:67], v68 offset:2048
	ds_read_b128 v[68:71], v68 offset:3072
	ds_read_b128 v[154:157], v166
	ds_read_b128 v[158:161], v166 offset:1024
	ds_read_b128 v[162:165], v166 offset:2048
	ds_read_b128 v[166:169], v166 offset:3072
	s_add_u32 s44, s52, 0x80000
	s_addc_u32 s45, s53, 0
	s_mov_b32 m0, s62
	v_lshl_add_u64 v[214:215], s[44:45], 0, v[148:149]
	ds_read_b128 v[170:173], v199 offset:32768
	ds_read_b128 v[174:177], v199 offset:33792
	ds_read_b128 v[178:181], v199 offset:34816
	ds_read_b128 v[182:185], v199 offset:35840
	ds_read_b128 v[186:189], v199 offset:36864
	ds_read_b128 v[194:197], v199 offset:37888
	ds_read_b128 v[200:203], v199 offset:38912
	ds_read_b128 v[204:207], v199 offset:39936
	global_load_lds_dwordx4 v[214:215], off
	v_lshl_add_u64 v[214:215], s[44:45], 0, v[146:147]
	s_mov_b32 m0, s63
	s_nop 0
	global_load_lds_dwordx4 v[214:215], off
	s_waitcnt vmcnt(8)
	s_waitcnt lgkmcnt(0)
	s_barrier
	s_setprio 1
	v_mfma_i32_16x16x64_i8 v[140:143], v[56:59], v[170:173], v[140:143]
	v_mfma_i32_16x16x64_i8 v[136:139], v[64:67], v[170:173], v[136:139]
	v_mfma_i32_16x16x64_i8 v[132:135], v[56:59], v[178:181], v[132:135]
	v_mfma_i32_16x16x64_i8 v[124:127], v[64:67], v[178:181], v[124:127]
	v_mfma_i32_16x16x64_i8 v[116:119], v[56:59], v[186:189], v[116:119]
	v_mfma_i32_16x16x64_i8 v[108:111], v[64:67], v[186:189], v[108:111]
	v_mfma_i32_16x16x64_i8 v[100:103], v[56:59], v[200:203], v[100:103]
	v_mfma_i32_16x16x64_i8 v[92:95], v[64:67], v[200:203], v[92:95]
	v_mfma_i32_16x16x64_i8 v[140:143], v[60:63], v[174:177], v[140:143]
	v_mfma_i32_16x16x64_i8 v[136:139], v[68:71], v[174:177], v[136:139]
	v_mfma_i32_16x16x64_i8 v[132:135], v[60:63], v[182:185], v[132:135]
	v_mfma_i32_16x16x64_i8 v[124:127], v[68:71], v[182:185], v[124:127]
	v_mfma_i32_16x16x64_i8 v[116:119], v[60:63], v[194:197], v[116:119]
	v_mfma_i32_16x16x64_i8 v[108:111], v[68:71], v[194:197], v[108:111]
	v_mfma_i32_16x16x64_i8 v[100:103], v[60:63], v[204:207], v[100:103]
	v_mfma_i32_16x16x64_i8 v[92:95], v[68:71], v[204:207], v[92:95]
	s_setprio 0
	s_setprio 1
	v_mfma_i32_16x16x64_i8 v[128:131], v[154:157], v[170:173], v[128:131]
	v_mfma_i32_16x16x64_i8 v[120:123], v[162:165], v[170:173], v[120:123]
	v_mfma_i32_16x16x64_i8 v[112:115], v[154:157], v[178:181], v[112:115]
	v_mfma_i32_16x16x64_i8 v[104:107], v[162:165], v[178:181], v[104:107]
	v_mfma_i32_16x16x64_i8 v[96:99], v[154:157], v[186:189], v[96:99]
	v_mfma_i32_16x16x64_i8 v[88:91], v[162:165], v[186:189], v[88:91]
	v_mfma_i32_16x16x64_i8 v[84:87], v[154:157], v[200:203], v[84:87]
	v_mfma_i32_16x16x64_i8 v[80:83], v[162:165], v[200:203], v[80:83]
	v_mfma_i32_16x16x64_i8 v[128:131], v[158:161], v[174:177], v[128:131]
	v_mfma_i32_16x16x64_i8 v[120:123], v[166:169], v[174:177], v[120:123]
	v_mfma_i32_16x16x64_i8 v[112:115], v[158:161], v[182:185], v[112:115]
	v_mfma_i32_16x16x64_i8 v[104:107], v[166:169], v[182:185], v[104:107]
	v_mfma_i32_16x16x64_i8 v[96:99], v[158:161], v[194:197], v[96:99]
	v_mfma_i32_16x16x64_i8 v[88:91], v[166:169], v[194:197], v[88:91]
	v_mfma_i32_16x16x64_i8 v[84:87], v[158:161], v[204:207], v[84:87]
	v_mfma_i32_16x16x64_i8 v[80:83], v[166:169], v[204:207], v[80:83]
	s_setprio 0
	s_barrier
; #define PG8_ITER_HEAD() \
;             const bool last = (t == nt - 2); \
;             const char* a1 = cA + (size_t)(t + 1) * kstep; \
;             const char* a2 = last ? nA : cA + (size_t)(t + 2) * kstep; const char* b2 = last ? nB : cB + (size_t)(t + 2) * kstep; \
;             const char* a3 = a2 + kstep; const char* b3 = b2 + kstep; \
;             if (last && has_next) S.a_ready(nxt);
;     ...
;             for (; t < nt; t += 2) { PG8_ITER_HEAD() PG8_ITER_SP2(PG8_MMAI) }
	s_add_i32 s12, s12, s0
	v_lshl_add_u64 v[190:191], v[190:191], 0, s[34:35]
	s_mov_b32 m0, s12
	ds_read_b128 v[170:173], v199 offset:49152
	ds_read_b128 v[174:177], v199 offset:50176
	ds_read_b128 v[178:181], v199 offset:51200
	ds_read_b128 v[182:185], v199 offset:52224
	ds_read_b128 v[186:189], v199 offset:53248
	ds_read_b128 v[194:197], v199 offset:54272
	ds_read_b128 v[200:203], v199 offset:55296
	ds_read_b128 v[204:207], v199 offset:56320
	global_load_lds_dwordx4 v[190:191], off
	s_add_i32 m0, s12, 0x2000
	s_add_u32 s24, s24, 0x80080
	v_lshl_add_u64 v[190:191], v[208:209], 0, s[34:35]
	s_addc_u32 s25, s25, 0
	s_add_i32 s12, s13, s0
	global_load_lds_dwordx4 v[190:191], off
	v_lshl_add_u64 v[190:191], s[24:25], 0, v[192:193]
	s_mov_b32 m0, s12
	s_nop 0
	global_load_lds_dwordx4 v[190:191], off
	v_lshl_add_u64 v[190:191], s[24:25], 0, v[144:145]
	s_add_i32 m0, s12, 0x2000
	s_nop 0
	global_load_lds_dwordx4 v[190:191], off
	v_lshl_add_u64 v[190:191], v[210:211], 0, s[34:35]
	s_mov_b32 m0, s74
	s_nop 0
	global_load_lds_dwordx4 v[190:191], off
	v_lshl_add_u64 v[190:191], v[212:213], 0, s[34:35]
	s_mov_b32 m0, s75
	s_nop 0
	global_load_lds_dwordx4 v[190:191], off
	s_waitcnt vmcnt(8)
	s_waitcnt lgkmcnt(0)
	s_barrier
	s_setprio 1
	v_mfma_i32_16x16x64_i8 v[76:79], v[56:59], v[170:173], v[76:79]
	v_mfma_i32_16x16x64_i8 v[72:75], v[64:67], v[170:173], v[72:75]
	v_mfma_i32_16x16x64_i8 v[52:55], v[56:59], v[178:181], v[52:55]
	v_mfma_i32_16x16x64_i8 v[44:47], v[64:67], v[178:181], v[44:47]
	v_mfma_i32_16x16x64_i8 v[36:39], v[56:59], v[186:189], v[36:39]
	v_mfma_i32_16x16x64_i8 v[24:27], v[64:67], v[186:189], v[24:27]
	v_mfma_i32_16x16x64_i8 v[12:15], v[56:59], v[200:203], v[12:15]
	v_mfma_i32_16x16x64_i8 v[4:7], v[64:67], v[200:203], v[4:7]
	v_mfma_i32_16x16x64_i8 v[76:79], v[60:63], v[174:177], v[76:79]
	v_mfma_i32_16x16x64_i8 v[72:75], v[68:71], v[174:177], v[72:75]
	v_mfma_i32_16x16x64_i8 v[52:55], v[60:63], v[182:185], v[52:55]
	v_mfma_i32_16x16x64_i8 v[44:47], v[68:71], v[182:185], v[44:47]
	v_mfma_i32_16x16x64_i8 v[36:39], v[60:63], v[194:197], v[36:39]
	v_mfma_i32_16x16x64_i8 v[24:27], v[68:71], v[194:197], v[24:27]
	v_mfma_i32_16x16x64_i8 v[12:15], v[60:63], v[204:207], v[12:15]
	v_mfma_i32_16x16x64_i8 v[4:7], v[68:71], v[204:207], v[4:7]
	s_setprio 0
	s_setprio 1
	v_mfma_i32_16x16x64_i8 v[20:23], v[154:157], v[170:173], v[20:23]
	v_mfma_i32_16x16x64_i8 v[68:71], v[158:161], v[174:177], v[20:23]
	v_mfma_i32_16x16x64_i8 v[20:23], v[162:165], v[170:173], v[32:35]
	v_mfma_i32_16x16x64_i8 v[64:67], v[166:169], v[174:177], v[20:23]
	v_mfma_i32_16x16x64_i8 v[20:23], v[154:157], v[178:181], v[48:51]
	v_mfma_i32_16x16x64_i8 v[48:51], v[158:161], v[182:185], v[20:23]
	v_mfma_i32_16x16x64_i8 v[20:23], v[162:165], v[178:181], v[40:43]
	v_mfma_i32_16x16x64_i8 v[40:43], v[166:169], v[182:185], v[20:23]
	v_mfma_i32_16x16x64_i8 v[20:23], v[154:157], v[186:189], v[28:31]
	v_mfma_i32_16x16x64_i8 v[16:19], v[162:165], v[186:189], v[16:19]
	v_mfma_i32_16x16x64_i8 v[8:11], v[154:157], v[200:203], v[8:11]
	v_mfma_i32_16x16x64_i8 v[0:3], v[162:165], v[200:203], v[0:3]
	v_mfma_i32_16x16x64_i8 v[28:31], v[158:161], v[194:197], v[20:23]
	v_mfma_i32_16x16x64_i8 v[16:19], v[166:169], v[194:197], v[16:19]
	v_mfma_i32_16x16x64_i8 v[8:11], v[158:161], v[204:207], v[8:11]
	v_mfma_i32_16x16x64_i8 v[0:3], v[166:169], v[204:207], v[0:3]
	s_setprio 0
	s_barrier
	s_add_i32 s29, s29, 2
	s_add_u32 s50, s50, 0x100
	s_addc_u32 s51, s51, 0
	s_add_u32 s10, s10, 0x100
	s_addc_u32 s11, s11, 0
	s_cmp_lt_u32 s29, 30
	s_cbranch_scc1 .LBB0_552
	s_andn2_b64 vcc, exec, s[38:39]
	s_cbranch_vccnz .LBB0_555
	s_barrier

; #define PG8_MMA(ai, bj, At, Bt) do { __builtin_amdgcn_s_setprio(1); _Pragma("unroll") for (int m = 0; m < 4; ++m) _Pragma("unroll") for (int n = 0; n < 2; ++n) _Pragma("unroll") for (int k = 0; k < 2; ++k) \
;         acc[ai][bj][m][n] = __builtin_amdgcn_mfma_f32_16x16x32_bf16(Bt[n][k], At[m][k], acc[ai][bj][m][n], 0, 0, 0); __builtin_amdgcn_s_setprio(0); } while (0)
; #define PG8_ITER_HEAD() \
;             const bool last = (t == nt - 2); \
;             const char* a1 = cA + (size_t)(t + 1) * kstep; \
;             const char* a2 = last ? nA : cA + (size_t)(t + 2) * kstep; const char* b2 = last ? nB : cB + (size_t)(t + 2) * kstep; \
;             const char* a3 = a2 + kstep; const char* b3 = b2 + kstep; \
;             if (last && has_next) S.a_ready(nxt);
;     ...
;             for (; t < KS8; t += 2) { PG8_ITER_HEAD() PG8_ITER_SP2(PG8_MMA) }
.LBB0_615:
	v_add_u32_e32 v128, 0x10000, v132
	v_add_u32_e32 v129, 0x14000, v132
	ds_read_b128 v[134:137], v128
	ds_read_b128 v[138:141], v128 offset:1024
	ds_read_b128 v[142:145], v128 offset:2048
	ds_read_b128 v[146:149], v128 offset:3072
	ds_read_b128 v[150:153], v129
	ds_read_b128 v[154:157], v129 offset:1024
	ds_read_b128 v[158:161], v129 offset:2048
	ds_read_b128 v[162:165], v129 offset:3072
	s_add_u32 s94, s60, 0x180
	s_addc_u32 s95, s61, 0
	s_add_u32 s62, s56, 0x100
	s_addc_u32 s63, s57, 0
	s_add_u32 s90, s60, 0x100
	s_addc_u32 s91, s61, 0
	ds_read_b128 v[166:169], v133
	ds_read_b128 v[170:173], v133 offset:1024
	ds_read_b128 v[174:177], v133 offset:2048
	ds_read_b128 v[178:181], v133 offset:3072
	ds_read_b128 v[182:185], v133 offset:4096
	ds_read_b128 v[186:189], v133 offset:5120
	ds_read_b128 v[194:197], v133 offset:6144
	ds_read_b128 v[198:201], v133 offset:7168
	s_add_u32 s12, s60, 0x188080
	s_addc_u32 s13, s61, 0
	s_mov_b32 s25, m0
	s_mov_b32 m0, s79
	s_nop 0
	global_load_lds_dwordx4 v130, s[12:13]
	s_mov_b32 m0, s25
	s_nop 0
	s_mov_b32 s25, m0
	s_mov_b32 m0, s96
	s_nop 0
	global_load_lds_dwordx4 v131, s[12:13]
	s_mov_b32 m0, s25
	s_waitcnt vmcnt(8)
	s_waitcnt lgkmcnt(0)
	s_barrier
	s_setprio 1
	v_mfma_f32_16x16x32_bf16 v[124:127], v[134:137], v[166:169], v[124:127]
	v_mfma_f32_16x16x32_bf16 v[120:123], v[142:145], v[166:169], v[120:123]
	v_mfma_f32_16x16x32_bf16 v[112:115], v[134:137], v[174:177], v[112:115]
	v_mfma_f32_16x16x32_bf16 v[104:107], v[142:145], v[174:177], v[104:107]
	v_mfma_f32_16x16x32_bf16 v[96:99], v[134:137], v[182:185], v[96:99]
	v_mfma_f32_16x16x32_bf16 v[88:91], v[142:145], v[182:185], v[88:91]
	v_mfma_f32_16x16x32_bf16 v[80:83], v[134:137], v[194:197], v[80:83]
	v_mfma_f32_16x16x32_bf16 v[72:75], v[142:145], v[194:197], v[72:75]
	v_mfma_f32_16x16x32_bf16 v[124:127], v[138:141], v[170:173], v[124:127]
	v_mfma_f32_16x16x32_bf16 v[120:123], v[146:149], v[170:173], v[120:123]
	v_mfma_f32_16x16x32_bf16 v[112:115], v[138:141], v[178:181], v[112:115]
	v_mfma_f32_16x16x32_bf16 v[104:107], v[146:149], v[178:181], v[104:107]
	v_mfma_f32_16x16x32_bf16 v[96:99], v[138:141], v[186:189], v[96:99]
	v_mfma_f32_16x16x32_bf16 v[88:91], v[146:149], v[186:189], v[88:91]
	v_mfma_f32_16x16x32_bf16 v[80:83], v[138:141], v[198:201], v[80:83]
	v_mfma_f32_16x16x32_bf16 v[72:75], v[146:149], v[198:201], v[72:75]
	s_setprio 0
	s_setprio 1
	v_mfma_f32_16x16x32_bf16 v[116:119], v[150:153], v[166:169], v[116:119]
	v_mfma_f32_16x16x32_bf16 v[108:111], v[158:161], v[166:169], v[108:111]
	v_mfma_f32_16x16x32_bf16 v[100:103], v[150:153], v[174:177], v[100:103]
	v_mfma_f32_16x16x32_bf16 v[92:95], v[158:161], v[174:177], v[92:95]
	v_mfma_f32_16x16x32_bf16 v[84:87], v[150:153], v[182:185], v[84:87]
	v_mfma_f32_16x16x32_bf16 v[76:79], v[158:161], v[182:185], v[76:79]
	v_mfma_f32_16x16x32_bf16 v[68:71], v[150:153], v[194:197], v[68:71]
	v_mfma_f32_16x16x32_bf16 v[64:67], v[158:161], v[194:197], v[64:67]
	v_mfma_f32_16x16x32_bf16 v[116:119], v[154:157], v[170:173], v[116:119]
	v_mfma_f32_16x16x32_bf16 v[108:111], v[162:165], v[170:173], v[108:111]
	v_mfma_f32_16x16x32_bf16 v[100:103], v[154:157], v[178:181], v[100:103]
	v_mfma_f32_16x16x32_bf16 v[92:95], v[162:165], v[178:181], v[92:95]
	v_mfma_f32_16x16x32_bf16 v[84:87], v[154:157], v[186:189], v[84:87]
	v_mfma_f32_16x16x32_bf16 v[76:79], v[162:165], v[186:189], v[76:79]
	v_mfma_f32_16x16x32_bf16 v[68:71], v[154:157], v[198:201], v[68:71]
	v_mfma_f32_16x16x32_bf16 v[64:67], v[162:165], v[198:201], v[64:67]
	s_setprio 0
	s_barrier
	ds_read_b128 v[166:169], v133 offset:16384
	ds_read_b128 v[170:173], v133 offset:17408
	ds_read_b128 v[174:177], v133 offset:18432
	ds_read_b128 v[178:181], v133 offset:19456
	ds_read_b128 v[182:185], v133 offset:20480
	ds_read_b128 v[186:189], v133 offset:21504
	ds_read_b128 v[194:197], v133 offset:22528
	ds_read_b128 v[198:201], v133 offset:23552
	s_mov_b32 s12, m0
	s_mov_b32 m0, s4
	s_nop 0
	global_load_lds_dwordx4 v130, s[62:63]
	s_mov_b32 m0, s12
	s_nop 0
	s_mov_b32 s12, m0
	s_mov_b32 m0, s5
	s_nop 0
	global_load_lds_dwordx4 v131, s[62:63]
	s_mov_b32 m0, s12
	s_add_u32 s12, s56, 0x188100
	s_addc_u32 s13, s57, 0
	s_mov_b32 s25, m0
	s_mov_b32 m0, s6
	s_nop 0
	global_load_lds_dwordx4 v130, s[12:13]
	s_mov_b32 m0, s25
	s_nop 0
	s_mov_b32 s25, m0
	s_mov_b32 m0, s7
	s_nop 0
	global_load_lds_dwordx4 v131, s[12:13]
	s_mov_b32 m0, s25
	s_mov_b32 s12, m0
	s_mov_b32 m0, s0
	s_nop 0
	global_load_lds_dwordx4 v130, s[90:91]
	s_mov_b32 m0, s12
	s_nop 0
	s_mov_b32 s12, m0
	s_mov_b32 m0, s44
	s_nop 0
	global_load_lds_dwordx4 v131, s[90:91]
	s_mov_b32 m0, s12
	s_waitcnt vmcnt(8)
	s_waitcnt lgkmcnt(0)
	s_barrier
	s_setprio 1
	v_mfma_f32_16x16x32_bf16 v[60:63], v[134:137], v[166:169], v[60:63]
	v_mfma_f32_16x16x32_bf16 v[56:59], v[142:145], v[166:169], v[56:59]
	v_mfma_f32_16x16x32_bf16 v[52:55], v[134:137], v[174:177], v[52:55]
	v_mfma_f32_16x16x32_bf16 v[40:43], v[142:145], v[174:177], v[40:43]
	v_mfma_f32_16x16x32_bf16 v[36:39], v[134:137], v[182:185], v[36:39]
	v_mfma_f32_16x16x32_bf16 v[24:27], v[142:145], v[182:185], v[24:27]
	v_mfma_f32_16x16x32_bf16 v[20:23], v[134:137], v[194:197], v[20:23]
	v_mfma_f32_16x16x32_bf16 v[8:11], v[142:145], v[194:197], v[8:11]
	v_mfma_f32_16x16x32_bf16 v[60:63], v[138:141], v[170:173], v[60:63]
	v_mfma_f32_16x16x32_bf16 v[56:59], v[146:149], v[170:173], v[56:59]
	v_mfma_f32_16x16x32_bf16 v[52:55], v[138:141], v[178:181], v[52:55]
	v_mfma_f32_16x16x32_bf16 v[40:43], v[146:149], v[178:181], v[40:43]
	v_mfma_f32_16x16x32_bf16 v[36:39], v[138:141], v[186:189], v[36:39]
	v_mfma_f32_16x16x32_bf16 v[24:27], v[146:149], v[186:189], v[24:27]
	v_mfma_f32_16x16x32_bf16 v[20:23], v[138:141], v[198:201], v[20:23]
	v_mfma_f32_16x16x32_bf16 v[8:11], v[146:149], v[198:201], v[8:11]
	s_setprio 0
	s_setprio 1
	v_mfma_f32_16x16x32_bf16 v[48:51], v[150:153], v[166:169], v[48:51]
	v_mfma_f32_16x16x32_bf16 v[44:47], v[158:161], v[166:169], v[44:47]
	v_mfma_f32_16x16x32_bf16 v[32:35], v[150:153], v[174:177], v[32:35]
	v_mfma_f32_16x16x32_bf16 v[28:31], v[158:161], v[174:177], v[28:31]
	v_mfma_f32_16x16x32_bf16 v[16:19], v[150:153], v[182:185], v[16:19]
	v_mfma_f32_16x16x32_bf16 v[12:15], v[158:161], v[182:185], v[12:15]
	v_mfma_f32_16x16x32_bf16 v[4:7], v[150:153], v[194:197], v[4:7]
	v_mfma_f32_16x16x32_bf16 v[0:3], v[158:161], v[194:197], v[0:3]
	v_mfma_f32_16x16x32_bf16 v[48:51], v[154:157], v[170:173], v[48:51]
	v_mfma_f32_16x16x32_bf16 v[44:47], v[162:165], v[170:173], v[44:47]
	v_mfma_f32_16x16x32_bf16 v[32:35], v[154:157], v[178:181], v[32:35]
	v_mfma_f32_16x16x32_bf16 v[28:31], v[162:165], v[178:181], v[28:31]
	v_mfma_f32_16x16x32_bf16 v[16:19], v[154:157], v[186:189], v[16:19]
	v_mfma_f32_16x16x32_bf16 v[12:15], v[162:165], v[186:189], v[12:15]
	v_mfma_f32_16x16x32_bf16 v[4:7], v[154:157], v[198:201], v[4:7]
	v_mfma_f32_16x16x32_bf16 v[0:3], v[162:165], v[198:201], v[0:3]
	s_setprio 0
	s_barrier
	v_add_u32_e32 v134, 0x18000, v132
	v_add_u32_e32 v135, 0x1c000, v132
	ds_read_b128 v[136:139], v134
	ds_read_b128 v[140:143], v134 offset:1024
	ds_read_b128 v[144:147], v134 offset:2048
	ds_read_b128 v[148:151], v134 offset:3072
	ds_read_b128 v[152:155], v135
	ds_read_b128 v[156:159], v135 offset:1024
	ds_read_b128 v[160:163], v135 offset:2048
	ds_read_b128 v[164:167], v135 offset:3072
	ds_read_b128 v[168:171], v133 offset:32768
	ds_read_b128 v[172:175], v133 offset:33792
	ds_read_b128 v[176:179], v133 offset:34816
	ds_read_b128 v[180:183], v133 offset:35840
	ds_read_b128 v[184:187], v133 offset:36864
	ds_read_b128 v[188:191], v133 offset:37888
	ds_read_b128 v[194:197], v133 offset:38912
	ds_read_b128 v[198:201], v133 offset:39936
	s_add_u32 s12, s60, 0x188100
	s_addc_u32 s13, s61, 0
	s_mov_b32 s25, m0
	s_mov_b32 m0, s45
	s_nop 0
	global_load_lds_dwordx4 v130, s[12:13]
	s_mov_b32 m0, s25
	s_nop 0
	s_mov_b32 s25, m0
	s_mov_b32 m0, s58
	s_nop 0
	global_load_lds_dwordx4 v131, s[12:13]
	s_mov_b32 m0, s25
	s_waitcnt vmcnt(8)
	s_waitcnt lgkmcnt(0)
	s_barrier
	s_setprio 1
	v_mfma_f32_16x16x32_bf16 v[124:127], v[136:139], v[168:171], v[124:127]
	v_mfma_f32_16x16x32_bf16 v[120:123], v[144:147], v[168:171], v[120:123]
	v_mfma_f32_16x16x32_bf16 v[112:115], v[136:139], v[176:179], v[112:115]
	v_mfma_f32_16x16x32_bf16 v[104:107], v[144:147], v[176:179], v[104:107]
	v_mfma_f32_16x16x32_bf16 v[96:99], v[136:139], v[184:187], v[96:99]
	v_mfma_f32_16x16x32_bf16 v[88:91], v[144:147], v[184:187], v[88:91]
	v_mfma_f32_16x16x32_bf16 v[80:83], v[136:139], v[194:197], v[80:83]
	v_mfma_f32_16x16x32_bf16 v[72:75], v[144:147], v[194:197], v[72:75]
	v_mfma_f32_16x16x32_bf16 v[124:127], v[140:143], v[172:175], v[124:127]
	v_mfma_f32_16x16x32_bf16 v[120:123], v[148:151], v[172:175], v[120:123]
	v_mfma_f32_16x16x32_bf16 v[112:115], v[140:143], v[180:183], v[112:115]
	v_mfma_f32_16x16x32_bf16 v[104:107], v[148:151], v[180:183], v[104:107]
	v_mfma_f32_16x16x32_bf16 v[96:99], v[140:143], v[188:191], v[96:99]
	v_mfma_f32_16x16x32_bf16 v[88:91], v[148:151], v[188:191], v[88:91]
	v_mfma_f32_16x16x32_bf16 v[80:83], v[140:143], v[198:201], v[80:83]
	v_mfma_f32_16x16x32_bf16 v[72:75], v[148:151], v[198:201], v[72:75]
	s_setprio 0
	s_setprio 1
	v_mfma_f32_16x16x32_bf16 v[116:119], v[152:155], v[168:171], v[116:119]
	v_mfma_f32_16x16x32_bf16 v[108:111], v[160:163], v[168:171], v[108:111]
	v_mfma_f32_16x16x32_bf16 v[100:103], v[152:155], v[176:179], v[100:103]
	v_mfma_f32_16x16x32_bf16 v[92:95], v[160:163], v[176:179], v[92:95]
	v_mfma_f32_16x16x32_bf16 v[84:87], v[152:155], v[184:187], v[84:87]
	v_mfma_f32_16x16x32_bf16 v[76:79], v[160:163], v[184:187], v[76:79]
	v_mfma_f32_16x16x32_bf16 v[68:71], v[152:155], v[194:197], v[68:71]
	v_mfma_f32_16x16x32_bf16 v[64:67], v[160:163], v[194:197], v[64:67]
	v_mfma_f32_16x16x32_bf16 v[116:119], v[156:159], v[172:175], v[116:119]
	v_mfma_f32_16x16x32_bf16 v[108:111], v[164:167], v[172:175], v[108:111]
	v_mfma_f32_16x16x32_bf16 v[100:103], v[156:159], v[180:183], v[100:103]
	v_mfma_f32_16x16x32_bf16 v[92:95], v[164:167], v[180:183], v[92:95]
	v_mfma_f32_16x16x32_bf16 v[84:87], v[156:159], v[188:191], v[84:87]
	v_mfma_f32_16x16x32_bf16 v[76:79], v[164:167], v[188:191], v[76:79]
	v_mfma_f32_16x16x32_bf16 v[68:71], v[156:159], v[198:201], v[68:71]
	v_mfma_f32_16x16x32_bf16 v[64:67], v[164:167], v[198:201], v[64:67]
	s_setprio 0
	s_barrier
; #define PG8_MMA(ai, bj, At, Bt) do { __builtin_amdgcn_s_setprio(1); _Pragma("unroll") for (int m = 0; m < 4; ++m) _Pragma("unroll") for (int n = 0; n < 2; ++n) _Pragma("unroll") for (int k = 0; k < 2; ++k) \
;         acc[ai][bj][m][n] = __builtin_amdgcn_mfma_f32_16x16x32_bf16(Bt[n][k], At[m][k], acc[ai][bj][m][n], 0, 0, 0); __builtin_amdgcn_s_setprio(0); } while (0)
; #define PG8_MMA8(ai, bj, At, Bt) do { __builtin_amdgcn_s_setprio(1); _Pragma("unroll") for (int m = 0; m < 4; ++m) _Pragma("unroll") for (int n = 0; n < 2; ++n) \
;         acc[ai][bj][m][n] = __builtin_amdgcn_mfma_scale_f32_16x16x128_f8f6f4(cat8(Bt[n][0], Bt[n][1]), cat8(At[m][0], At[m][1]), acc[ai][bj][m][n], 0, 0, 0, F8_SC_W, 0, F8_SC_H); __builtin_amdgcn_s_setprio(0); } while (0)
; #define PG8_ITER_HEAD() \
;             const bool last = (t == nt - 2); \
;             const char* a1 = cA + (size_t)(t + 1) * kstep; \
;             const char* a2 = last ? nA : cA + (size_t)(t + 2) * kstep; const char* b2 = last ? nB : cB + (size_t)(t + 2) * kstep; \
;             const char* a3 = a2 + kstep; const char* b3 = b2 + kstep; \
;             if (last && has_next) S.a_ready(nxt);
;     ...
;             for (; t < KS8; t += 2) { PG8_ITER_HEAD() PG8_ITER_SP2(PG8_MMA) }
;             for (; t < nt; t += 2) { PG8_ITER_HEAD() PG8_ITER_SP2(PG8_MMA8) }
	ds_read_b128 v[168:171], v133 offset:49152
	ds_read_b128 v[172:175], v133 offset:50176
	ds_read_b128 v[176:179], v133 offset:51200
	ds_read_b128 v[180:183], v133 offset:52224
	ds_read_b128 v[184:187], v133 offset:53248
	ds_read_b128 v[188:191], v133 offset:54272
	ds_read_b128 v[194:197], v133 offset:55296
	ds_read_b128 v[198:201], v133 offset:56320
	s_add_u32 s12, s56, 0x180
	s_addc_u32 s13, s57, 0
	s_mov_b32 s25, m0
	s_mov_b32 m0, s73
	s_nop 0
	global_load_lds_dwordx4 v130, s[12:13]
	s_mov_b32 m0, s25
	s_nop 0
	s_mov_b32 s25, m0
	s_mov_b32 m0, s74
	s_nop 0
	global_load_lds_dwordx4 v131, s[12:13]
	s_mov_b32 m0, s25
	s_add_u32 s12, s56, 0x188180
	s_addc_u32 s13, s57, 0
	s_mov_b32 s25, m0
	s_mov_b32 m0, s77
	s_nop 0
	global_load_lds_dwordx4 v130, s[12:13]
	s_mov_b32 m0, s25
	s_nop 0
	s_mov_b32 s25, m0
	s_mov_b32 m0, s78
	s_nop 0
	global_load_lds_dwordx4 v131, s[12:13]
	s_mov_b32 m0, s25
	s_mov_b32 s12, m0
	s_mov_b32 m0, s75
	s_nop 0
	global_load_lds_dwordx4 v130, s[94:95]
	s_mov_b32 m0, s12
	s_nop 0
	s_mov_b32 s12, m0
	s_mov_b32 m0, s76
	s_nop 0
	global_load_lds_dwordx4 v131, s[94:95]
	s_mov_b32 m0, s12
	s_waitcnt vmcnt(8)
	s_waitcnt lgkmcnt(0)
	s_barrier
	s_setprio 1
	v_mfma_f32_16x16x32_bf16 v[60:63], v[136:139], v[168:171], v[60:63]
	v_mfma_f32_16x16x32_bf16 v[56:59], v[144:147], v[168:171], v[56:59]
	v_mfma_f32_16x16x32_bf16 v[52:55], v[136:139], v[176:179], v[52:55]
	v_mfma_f32_16x16x32_bf16 v[40:43], v[144:147], v[176:179], v[40:43]
	v_mfma_f32_16x16x32_bf16 v[36:39], v[136:139], v[184:187], v[36:39]
	v_mfma_f32_16x16x32_bf16 v[24:27], v[144:147], v[184:187], v[24:27]
	v_mfma_f32_16x16x32_bf16 v[20:23], v[136:139], v[194:197], v[20:23]
	v_mfma_f32_16x16x32_bf16 v[8:11], v[144:147], v[194:197], v[8:11]
	v_mfma_f32_16x16x32_bf16 v[60:63], v[140:143], v[172:175], v[60:63]
	v_mfma_f32_16x16x32_bf16 v[56:59], v[148:151], v[172:175], v[56:59]
	v_mfma_f32_16x16x32_bf16 v[52:55], v[140:143], v[180:183], v[52:55]
	v_mfma_f32_16x16x32_bf16 v[40:43], v[148:151], v[180:183], v[40:43]
	v_mfma_f32_16x16x32_bf16 v[36:39], v[140:143], v[188:191], v[36:39]
	v_mfma_f32_16x16x32_bf16 v[24:27], v[148:151], v[188:191], v[24:27]
	v_mfma_f32_16x16x32_bf16 v[20:23], v[140:143], v[198:201], v[20:23]
	v_mfma_f32_16x16x32_bf16 v[8:11], v[148:151], v[198:201], v[8:11]
	s_setprio 0
	s_setprio 1
	v_mfma_f32_16x16x32_bf16 v[48:51], v[152:155], v[168:171], v[48:51]
	v_mfma_f32_16x16x32_bf16 v[44:47], v[160:163], v[168:171], v[44:47]
	v_mfma_f32_16x16x32_bf16 v[32:35], v[152:155], v[176:179], v[32:35]
	v_mfma_f32_16x16x32_bf16 v[28:31], v[160:163], v[176:179], v[28:31]
	v_mfma_f32_16x16x32_bf16 v[16:19], v[152:155], v[184:187], v[16:19]
	v_mfma_f32_16x16x32_bf16 v[12:15], v[160:163], v[184:187], v[12:15]
	v_mfma_f32_16x16x32_bf16 v[4:7], v[152:155], v[194:197], v[4:7]
	v_mfma_f32_16x16x32_bf16 v[0:3], v[160:163], v[194:197], v[0:3]
	v_mfma_f32_16x16x32_bf16 v[48:51], v[156:159], v[172:175], v[48:51]
	v_mfma_f32_16x16x32_bf16 v[44:47], v[164:167], v[172:175], v[44:47]
	v_mfma_f32_16x16x32_bf16 v[32:35], v[156:159], v[180:183], v[32:35]
	v_mfma_f32_16x16x32_bf16 v[28:31], v[164:167], v[180:183], v[28:31]
	v_mfma_f32_16x16x32_bf16 v[16:19], v[156:159], v[188:191], v[16:19]
	v_mfma_f32_16x16x32_bf16 v[12:15], v[164:167], v[188:191], v[12:15]
	v_mfma_f32_16x16x32_bf16 v[4:7], v[156:159], v[198:201], v[4:7]
	v_mfma_f32_16x16x32_bf16 v[0:3], v[164:167], v[198:201], v[0:3]
	s_setprio 0
	s_barrier
	s_add_i32 s24, s24, 2
	s_cmp_lt_u32 s24, 22
	s_mov_b64 s[56:57], s[62:63]
	s_mov_b64 s[60:61], s[90:91]
	s_cbranch_scc1 .LBB0_615
	s_add_u32 s60, s52, 0xc00
	s_addc_u32 s61, s53, 0
	s_add_u32 s62, s50, 0xd00
	s_addc_u32 s63, s51, 0
	s_mov_b32 s90, 22
.LBB0_617:
	ds_read_b128 v[136:139], v128
	ds_read_b128 v[140:143], v128 offset:1024
	ds_read_b128 v[144:147], v128 offset:2048
	ds_read_b128 v[148:151], v128 offset:3072
	ds_read_b128 v[152:155], v129
	ds_read_b128 v[156:159], v129 offset:1024
	ds_read_b128 v[160:163], v129 offset:2048
	ds_read_b128 v[164:167], v129 offset:3072
	s_add_u32 s50, s60, 0x100
	s_addc_u32 s51, s61, 0
	s_cmpk_eq_i32 s90, 0x5e
	s_cselect_b32 s24, s40, s50
	s_cselect_b32 s25, s41, s51
	s_cselect_b32 s56, s46, s62
	s_cselect_b32 s57, s47, s63
	s_add_u32 s52, s24, 0x80
	s_addc_u32 s53, s25, 0
	ds_read_b128 v[168:171], v133
	ds_read_b128 v[172:175], v133 offset:1024
	ds_read_b128 v[176:179], v133 offset:2048
	ds_read_b128 v[180:183], v133 offset:3072
	ds_read_b128 v[184:187], v133 offset:4096
	ds_read_b128 v[188:191], v133 offset:5120
	ds_read_b128 v[198:201], v133 offset:6144
	ds_read_b128 v[202:205], v133 offset:7168
	s_add_u32 s12, s60, 0x188080
	s_addc_u32 s13, s61, 0
	s_mov_b32 s60, m0
	s_mov_b32 m0, s79
	s_nop 0
	global_load_lds_dwordx4 v130, s[12:13]
	s_mov_b32 m0, s60
	s_nop 0
	s_mov_b32 s60, m0
	s_mov_b32 m0, s96
	s_nop 0
	global_load_lds_dwordx4 v131, s[12:13]
	s_mov_b32 m0, s60
	s_waitcnt vmcnt(8)
	s_waitcnt lgkmcnt(0)
	s_barrier
	s_setprio 1
	v_mfma_scale_f32_16x16x128_f8f6f4 v[124:127], v[136:143], v[168:175], v[124:127], v219, v218 op_sel_hi:[0,0,0]
	v_mfma_scale_f32_16x16x128_f8f6f4 v[120:123], v[144:151], v[168:175], v[120:123], v219, v218 op_sel_hi:[0,0,0]
	v_mfma_scale_f32_16x16x128_f8f6f4 v[112:115], v[136:143], v[176:183], v[112:115], v219, v218 op_sel_hi:[0,0,0]
	v_mfma_scale_f32_16x16x128_f8f6f4 v[104:107], v[144:151], v[176:183], v[104:107], v219, v218 op_sel_hi:[0,0,0]
	v_mfma_scale_f32_16x16x128_f8f6f4 v[96:99], v[136:143], v[184:191], v[96:99], v219, v218 op_sel_hi:[0,0,0]
	v_mfma_scale_f32_16x16x128_f8f6f4 v[194:197], v[144:151], v[184:191], v[88:91], v219, v218 op_sel_hi:[0,0,0]
	v_mfma_scale_f32_16x16x128_f8f6f4 v[206:209], v[136:143], v[198:205], v[80:83], v219, v218 op_sel_hi:[0,0,0]
	v_mfma_scale_f32_16x16x128_f8f6f4 v[210:213], v[144:151], v[198:205], v[72:75], v219, v218 op_sel_hi:[0,0,0]
	s_setprio 0
	s_setprio 1
	v_mfma_scale_f32_16x16x128_f8f6f4 v[116:119], v[152:159], v[168:175], v[116:119], v219, v218 op_sel_hi:[0,0,0]
	v_mfma_scale_f32_16x16x128_f8f6f4 v[108:111], v[160:167], v[168:175], v[108:111], v219, v218 op_sel_hi:[0,0,0]
	v_mfma_scale_f32_16x16x128_f8f6f4 v[100:103], v[152:159], v[176:183], v[100:103], v219, v218 op_sel_hi:[0,0,0]
	v_mfma_scale_f32_16x16x128_f8f6f4 v[168:171], v[160:167], v[176:183], v[92:95], v219, v218 op_sel_hi:[0,0,0]
	v_mfma_scale_f32_16x16x128_f8f6f4 v[172:175], v[152:159], v[184:191], v[84:87], v219, v218 op_sel_hi:[0,0,0]
	v_mfma_scale_f32_16x16x128_f8f6f4 v[176:179], v[160:167], v[184:191], v[76:79], v219, v218 op_sel_hi:[0,0,0]
	v_mfma_scale_f32_16x16x128_f8f6f4 v[180:183], v[152:159], v[198:205], v[68:71], v219, v218 op_sel_hi:[0,0,0]
	v_mfma_scale_f32_16x16x128_f8f6f4 v[184:187], v[160:167], v[198:205], v[64:67], v219, v218 op_sel_hi:[0,0,0]
	s_setprio 0
	s_barrier
	s_nop 4
	ds_read_b128 v[64:67], v133 offset:16384
	ds_read_b128 v[68:71], v133 offset:17408
	ds_read_b128 v[72:75], v133 offset:18432
	ds_read_b128 v[76:79], v133 offset:19456
	ds_read_b128 v[80:83], v133 offset:20480
	ds_read_b128 v[84:87], v133 offset:21504
	ds_read_b128 v[88:91], v133 offset:22528
	ds_read_b128 v[92:95], v133 offset:23552
	s_mov_b32 s12, m0
	s_mov_b32 m0, s4
	s_nop 0
	global_load_lds_dwordx4 v130, s[56:57]
	s_mov_b32 m0, s12
	s_nop 0
	s_mov_b32 s12, m0
	s_mov_b32 m0, s5
	s_nop 0
	global_load_lds_dwordx4 v131, s[56:57]
	s_mov_b32 m0, s12
	s_add_u32 s12, s56, 0x188000
	s_addc_u32 s13, s57, 0
	s_mov_b32 s60, m0
	s_mov_b32 m0, s6
	s_nop 0
	global_load_lds_dwordx4 v130, s[12:13]
	s_mov_b32 m0, s60
	s_nop 0
	s_mov_b32 s60, m0
	s_mov_b32 m0, s7
	s_nop 0
	global_load_lds_dwordx4 v131, s[12:13]
	s_mov_b32 m0, s60
	s_mov_b32 s12, m0
	s_mov_b32 m0, s0
	s_nop 0
	global_load_lds_dwordx4 v130, s[24:25]
	s_mov_b32 m0, s12
	s_nop 0
	s_mov_b32 s12, m0
	s_mov_b32 m0, s44
	s_nop 0
	global_load_lds_dwordx4 v131, s[24:25]
	s_mov_b32 m0, s12
	s_waitcnt vmcnt(8)
	s_waitcnt lgkmcnt(0)
	s_barrier
	s_setprio 1
	v_mfma_scale_f32_16x16x128_f8f6f4 v[60:63], v[136:143], v[64:71], v[60:63], v219, v218 op_sel_hi:[0,0,0]
	v_mfma_scale_f32_16x16x128_f8f6f4 v[56:59], v[144:151], v[64:71], v[56:59], v219, v218 op_sel_hi:[0,0,0]
	v_mfma_scale_f32_16x16x128_f8f6f4 v[52:55], v[136:143], v[72:79], v[52:55], v219, v218 op_sel_hi:[0,0,0]
	v_mfma_scale_f32_16x16x128_f8f6f4 v[188:191], v[144:151], v[72:79], v[40:43], v219, v218 op_sel_hi:[0,0,0]
	v_mfma_scale_f32_16x16x128_f8f6f4 v[198:201], v[136:143], v[80:87], v[36:39], v219, v218 op_sel_hi:[0,0,0]
	v_mfma_scale_f32_16x16x128_f8f6f4 v[202:205], v[144:151], v[80:87], v[24:27], v219, v218 op_sel_hi:[0,0,0]
	v_mfma_scale_f32_16x16x128_f8f6f4 v[214:217], v[136:143], v[88:95], v[20:23], v219, v218 op_sel_hi:[0,0,0]
	v_mfma_scale_f32_16x16x128_f8f6f4 v[220:223], v[144:151], v[88:95], v[8:11], v219, v218 op_sel_hi:[0,0,0]
	s_setprio 0
	s_setprio 1
	v_mfma_scale_f32_16x16x128_f8f6f4 v[48:51], v[152:159], v[64:71], v[48:51], v219, v218 op_sel_hi:[0,0,0]
	v_mfma_scale_f32_16x16x128_f8f6f4 v[224:227], v[160:167], v[64:71], v[44:47], v219, v218 op_sel_hi:[0,0,0]
	v_mfma_scale_f32_16x16x128_f8f6f4 v[228:231], v[152:159], v[72:79], v[32:35], v219, v218 op_sel_hi:[0,0,0]
	v_mfma_scale_f32_16x16x128_f8f6f4 v[232:235], v[160:167], v[72:79], v[28:31], v219, v218 op_sel_hi:[0,0,0]
	v_mfma_scale_f32_16x16x128_f8f6f4 v[236:239], v[152:159], v[80:87], v[16:19], v219, v218 op_sel_hi:[0,0,0]
	v_mfma_scale_f32_16x16x128_f8f6f4 v[240:243], v[160:167], v[80:87], v[12:15], v219, v218 op_sel_hi:[0,0,0]
	v_mfma_scale_f32_16x16x128_f8f6f4 v[244:247], v[152:159], v[88:95], v[4:7], v219, v218 op_sel_hi:[0,0,0]
	v_mfma_scale_f32_16x16x128_f8f6f4 v[248:251], v[160:167], v[88:95], v[0:3], v219, v218 op_sel_hi:[0,0,0]
	s_setprio 0
	s_barrier
	s_nop 4
	ds_read_b128 v[0:3], v134
	ds_read_b128 v[4:7], v134 offset:1024
	ds_read_b128 v[8:11], v134 offset:2048
	ds_read_b128 v[12:15], v134 offset:3072
	ds_read_b128 v[136:139], v135
	ds_read_b128 v[140:143], v135 offset:1024
	ds_read_b128 v[144:147], v135 offset:2048
	ds_read_b128 v[148:151], v135 offset:3072
	ds_read_b128 v[16:19], v133 offset:32768
	ds_read_b128 v[20:23], v133 offset:33792
	ds_read_b128 v[24:27], v133 offset:34816
	ds_read_b128 v[28:31], v133 offset:35840
	ds_read_b128 v[32:35], v133 offset:36864
	ds_read_b128 v[36:39], v133 offset:37888
	ds_read_b128 v[40:43], v133 offset:38912
	ds_read_b128 v[44:47], v133 offset:39936
	s_add_u32 s12, s24, 0x188000
	s_addc_u32 s13, s25, 0
	s_mov_b32 s24, m0
	s_mov_b32 m0, s45
	s_nop 0
	global_load_lds_dwordx4 v130, s[12:13]
	s_mov_b32 m0, s24
	s_nop 0
	s_mov_b32 s24, m0
	s_mov_b32 m0, s58
	s_nop 0
	global_load_lds_dwordx4 v131, s[12:13]
	s_mov_b32 m0, s24
	s_waitcnt vmcnt(8)
	s_waitcnt lgkmcnt(0)
	s_barrier
; #define PG8_MMA8(ai, bj, At, Bt) do { __builtin_amdgcn_s_setprio(1); _Pragma("unroll") for (int m = 0; m < 4; ++m) _Pragma("unroll") for (int n = 0; n < 2; ++n) \
;         acc[ai][bj][m][n] = __builtin_amdgcn_mfma_scale_f32_16x16x128_f8f6f4(cat8(Bt[n][0], Bt[n][1]), cat8(At[m][0], At[m][1]), acc[ai][bj][m][n], 0, 0, 0, F8_SC_W, 0, F8_SC_H); __builtin_amdgcn_s_setprio(0); } while (0)
; #define PG8_ITER_HEAD() \
;             const bool last = (t == nt - 2); \
;             const char* a1 = cA + (size_t)(t + 1) * kstep; \
;             const char* a2 = last ? nA : cA + (size_t)(t + 2) * kstep; const char* b2 = last ? nB : cB + (size_t)(t + 2) * kstep; \
;             const char* a3 = a2 + kstep; const char* b3 = b2 + kstep; \
;             if (last && has_next) S.a_ready(nxt);
;     ...
;             for (; t < nt; t += 2) { PG8_ITER_HEAD() PG8_ITER_SP2(PG8_MMA8) }
	s_setprio 1
	v_mfma_scale_f32_16x16x128_f8f6f4 v[124:127], v[0:7], v[16:23], v[124:127], v219, v218 op_sel_hi:[0,0,0]
	v_mfma_scale_f32_16x16x128_f8f6f4 v[120:123], v[8:15], v[16:23], v[120:123], v219, v218 op_sel_hi:[0,0,0]
	v_mfma_scale_f32_16x16x128_f8f6f4 v[112:115], v[0:7], v[24:31], v[112:115], v219, v218 op_sel_hi:[0,0,0]
	v_mfma_scale_f32_16x16x128_f8f6f4 v[104:107], v[8:15], v[24:31], v[104:107], v219, v218 op_sel_hi:[0,0,0]
	v_mfma_scale_f32_16x16x128_f8f6f4 v[96:99], v[0:7], v[32:39], v[96:99], v219, v218 op_sel_hi:[0,0,0]
	v_mfma_scale_f32_16x16x128_f8f6f4 v[88:91], v[8:15], v[32:39], v[194:197], v219, v218 op_sel_hi:[0,0,0]
	v_mfma_scale_f32_16x16x128_f8f6f4 v[80:83], v[0:7], v[40:47], v[206:209], v219, v218 op_sel_hi:[0,0,0]
	v_mfma_scale_f32_16x16x128_f8f6f4 v[72:75], v[8:15], v[40:47], v[210:213], v219, v218 op_sel_hi:[0,0,0]
	s_setprio 0
	s_setprio 1
	v_mfma_scale_f32_16x16x128_f8f6f4 v[116:119], v[136:143], v[16:23], v[116:119], v219, v218 op_sel_hi:[0,0,0]
	v_mfma_scale_f32_16x16x128_f8f6f4 v[108:111], v[144:151], v[16:23], v[108:111], v219, v218 op_sel_hi:[0,0,0]
	v_mfma_scale_f32_16x16x128_f8f6f4 v[100:103], v[136:143], v[24:31], v[100:103], v219, v218 op_sel_hi:[0,0,0]
	v_mfma_scale_f32_16x16x128_f8f6f4 v[92:95], v[144:151], v[24:31], v[168:171], v219, v218 op_sel_hi:[0,0,0]
	v_mfma_scale_f32_16x16x128_f8f6f4 v[84:87], v[136:143], v[32:39], v[172:175], v219, v218 op_sel_hi:[0,0,0]
	v_mfma_scale_f32_16x16x128_f8f6f4 v[76:79], v[144:151], v[32:39], v[176:179], v219, v218 op_sel_hi:[0,0,0]
	v_mfma_scale_f32_16x16x128_f8f6f4 v[68:71], v[136:143], v[40:47], v[180:183], v219, v218 op_sel_hi:[0,0,0]
	v_mfma_scale_f32_16x16x128_f8f6f4 v[64:67], v[144:151], v[40:47], v[184:187], v219, v218 op_sel_hi:[0,0,0]
	s_setprio 0
	s_barrier
	ds_read_b128 v[28:31], v133 offset:49152
	ds_read_b128 v[32:35], v133 offset:50176
	ds_read_b128 v[152:155], v133 offset:51200
	ds_read_b128 v[156:159], v133 offset:52224
	ds_read_b128 v[160:163], v133 offset:53248
	ds_read_b128 v[164:167], v133 offset:54272
	ds_read_b128 v[168:171], v133 offset:55296
	ds_read_b128 v[172:175], v133 offset:56320
	s_add_u32 s12, s56, 0x80
	s_addc_u32 s13, s57, 0
	s_mov_b32 s24, m0
	s_mov_b32 m0, s73
	s_nop 0
	global_load_lds_dwordx4 v130, s[12:13]
	s_mov_b32 m0, s24
	s_nop 0
	s_mov_b32 s24, m0
	s_mov_b32 m0, s74
	s_nop 0
	global_load_lds_dwordx4 v131, s[12:13]
	s_mov_b32 m0, s24
	s_add_u32 s12, s56, 0x188080
	s_addc_u32 s13, s57, 0
	s_mov_b32 s24, m0
	s_mov_b32 m0, s77
	s_nop 0
	global_load_lds_dwordx4 v130, s[12:13]
	s_mov_b32 m0, s24
	s_nop 0
	s_mov_b32 s24, m0
	s_mov_b32 m0, s78
	s_nop 0
	global_load_lds_dwordx4 v131, s[12:13]
	s_mov_b32 m0, s24
	s_mov_b32 s12, m0
	s_mov_b32 m0, s75
	s_nop 0
	global_load_lds_dwordx4 v130, s[52:53]
	s_mov_b32 m0, s12
	s_nop 0
	s_mov_b32 s12, m0
	s_mov_b32 m0, s76
	s_nop 0
	global_load_lds_dwordx4 v131, s[52:53]
	s_mov_b32 m0, s12
	s_waitcnt vmcnt(8)
	s_waitcnt lgkmcnt(0)
	s_barrier
	s_setprio 1
	v_mfma_scale_f32_16x16x128_f8f6f4 v[60:63], v[0:7], v[28:35], v[60:63], v219, v218 op_sel_hi:[0,0,0]
	v_mfma_scale_f32_16x16x128_f8f6f4 v[56:59], v[8:15], v[28:35], v[56:59], v219, v218 op_sel_hi:[0,0,0]
	v_mfma_scale_f32_16x16x128_f8f6f4 v[52:55], v[0:7], v[152:159], v[52:55], v219, v218 op_sel_hi:[0,0,0]
	v_mfma_scale_f32_16x16x128_f8f6f4 v[40:43], v[8:15], v[152:159], v[188:191], v219, v218 op_sel_hi:[0,0,0]
	v_mfma_scale_f32_16x16x128_f8f6f4 v[36:39], v[0:7], v[160:167], v[198:201], v219, v218 op_sel_hi:[0,0,0]
	v_mfma_scale_f32_16x16x128_f8f6f4 v[24:27], v[8:15], v[160:167], v[202:205], v219, v218 op_sel_hi:[0,0,0]
	v_mfma_scale_f32_16x16x128_f8f6f4 v[20:23], v[0:7], v[168:175], v[214:217], v219, v218 op_sel_hi:[0,0,0]
	v_mfma_scale_f32_16x16x128_f8f6f4 v[8:11], v[8:15], v[168:175], v[220:223], v219, v218 op_sel_hi:[0,0,0]
	s_setprio 0
	s_setprio 1
	v_mfma_scale_f32_16x16x128_f8f6f4 v[48:51], v[136:143], v[28:35], v[48:51], v219, v218 op_sel_hi:[0,0,0]
	v_mfma_scale_f32_16x16x128_f8f6f4 v[44:47], v[144:151], v[28:35], v[224:227], v219, v218 op_sel_hi:[0,0,0]
	v_mfma_scale_f32_16x16x128_f8f6f4 v[32:35], v[136:143], v[152:159], v[228:231], v219, v218 op_sel_hi:[0,0,0]
	v_mfma_scale_f32_16x16x128_f8f6f4 v[28:31], v[144:151], v[152:159], v[232:235], v219, v218 op_sel_hi:[0,0,0]
	v_mfma_scale_f32_16x16x128_f8f6f4 v[16:19], v[136:143], v[160:167], v[236:239], v219, v218 op_sel_hi:[0,0,0]
	v_mfma_scale_f32_16x16x128_f8f6f4 v[12:15], v[144:151], v[160:167], v[240:243], v219, v218 op_sel_hi:[0,0,0]
	v_mfma_scale_f32_16x16x128_f8f6f4 v[4:7], v[136:143], v[168:175], v[244:247], v219, v218 op_sel_hi:[0,0,0]
	v_mfma_scale_f32_16x16x128_f8f6f4 v[0:3], v[144:151], v[168:175], v[248:251], v219, v218 op_sel_hi:[0,0,0]
	s_setprio 0
	s_barrier
	s_add_i32 s90, s90, 2
	s_add_u32 s62, s62, 0x100
	s_addc_u32 s63, s63, 0
	s_cmpk_lt_u32 s90, 0x60
	s_mov_b64 s[60:61], s[50:51]
	s_cbranch_scc1 .LBB0_617
	v_readlane_b32 s90, v255, 19
	v_readlane_b32 s94, v255, 21
	s_andn2_b64 vcc, exec, s[42:43]
	v_readlane_b32 s91, v255, 20
	v_readlane_b32 s95, v255, 22
	s_cbranch_vccnz .LBB0_620
	s_barrier
